# combination: flattened barrier release + static priority for waves 4-7 + LDS read bases kept in spare VGPRs (GEMM1-3)
# baseline (speedup 1.0000x reference)
.Lkprio_0:
	ds_read_b128 v[146:149], v166
	ds_read_b128 v[150:153], v166 offset:1024
	ds_read_b128 v[154:157], v166 offset:2048
	ds_read_b128 v[170:173], v166 offset:3072
	ds_read_b128 v[174:177], v167
	ds_read_b128 v[178:181], v167 offset:1024
	ds_read_b128 v[182:185], v167 offset:2048
	ds_read_b128 v[186:189], v167 offset:3072
	s_add_u32 s76, s74, 0xfff80080
	s_addc_u32 s77, s75, -1
	s_cmp_eq_u32 s90, 28
	s_cselect_b32 s79, s0, s77
	s_cselect_b32 s78, s1, s76
	s_cselect_b32 s77, s3, s71
	s_cselect_b32 s76, s63, s65
	s_add_i32 m0, s31, 0xc000
	ds_read_b128 v[190:193], v168
	ds_read_b128 v[194:197], v168 offset:1024
	ds_read_b128 v[198:201], v168 offset:2048
	ds_read_b128 v[202:205], v168 offset:3072
	ds_read_b128 v[206:209], v168 offset:4096
	ds_read_b128 v[214:217], v168 offset:5120
	ds_read_b128 v[218:221], v168 offset:6144
	ds_read_b128 v[222:225], v168 offset:7168
	global_load_lds_dwordx4 v138, s[74:75]
	s_add_i32 m0, s31, 0xe000
	s_nop 0
	global_load_lds_dwordx4 v140, s[74:75]
	s_waitcnt vmcnt(8)
	s_waitcnt lgkmcnt(0)
	s_barrier
	v_mfma_f32_16x16x32_bf16 v[124:127], v[146:149], v[190:193], 0
	v_mfma_f32_16x16x32_bf16 v[120:123], v[154:157], v[190:193], 0
	v_mfma_f32_16x16x32_bf16 v[108:111], v[146:149], v[198:201], 0
	v_mfma_f32_16x16x32_bf16 v[104:107], v[154:157], v[198:201], 0
	v_mfma_f32_16x16x32_bf16 v[92:95], v[146:149], v[206:209], 0
	v_mfma_f32_16x16x32_bf16 v[88:91], v[154:157], v[206:209], 0
	v_mfma_f32_16x16x32_bf16 v[76:79], v[146:149], v[218:221], 0
	v_mfma_f32_16x16x32_bf16 v[72:75], v[154:157], v[218:221], 0
	v_mfma_f32_16x16x32_bf16 v[124:127], v[150:153], v[194:197], v[124:127]
	v_mfma_f32_16x16x32_bf16 v[120:123], v[170:173], v[194:197], v[120:123]
	v_mfma_f32_16x16x32_bf16 v[108:111], v[150:153], v[202:205], v[108:111]
	v_mfma_f32_16x16x32_bf16 v[104:107], v[170:173], v[202:205], v[104:107]
	v_mfma_f32_16x16x32_bf16 v[92:95], v[150:153], v[214:217], v[92:95]
	v_mfma_f32_16x16x32_bf16 v[88:91], v[170:173], v[214:217], v[88:91]
	v_mfma_f32_16x16x32_bf16 v[76:79], v[150:153], v[222:225], v[76:79]
	v_mfma_f32_16x16x32_bf16 v[72:75], v[170:173], v[222:225], v[72:75]
	v_mfma_f32_16x16x32_bf16 v[116:119], v[174:177], v[190:193], 0
	v_mfma_f32_16x16x32_bf16 v[112:115], v[182:185], v[190:193], 0
	v_mfma_f32_16x16x32_bf16 v[100:103], v[174:177], v[198:201], 0
	v_mfma_f32_16x16x32_bf16 v[96:99], v[182:185], v[198:201], 0
	v_mfma_f32_16x16x32_bf16 v[84:87], v[174:177], v[206:209], 0
	v_mfma_f32_16x16x32_bf16 v[80:83], v[182:185], v[206:209], 0
	v_mfma_f32_16x16x32_bf16 v[68:71], v[174:177], v[218:221], 0
	v_mfma_f32_16x16x32_bf16 v[64:67], v[182:185], v[218:221], 0
	v_mfma_f32_16x16x32_bf16 v[116:119], v[178:181], v[194:197], v[116:119]
	v_mfma_f32_16x16x32_bf16 v[112:115], v[186:189], v[194:197], v[112:115]
	v_mfma_f32_16x16x32_bf16 v[100:103], v[178:181], v[202:205], v[100:103]
	v_mfma_f32_16x16x32_bf16 v[96:99], v[186:189], v[202:205], v[96:99]
	v_mfma_f32_16x16x32_bf16 v[84:87], v[178:181], v[214:217], v[84:87]
	v_mfma_f32_16x16x32_bf16 v[80:83], v[186:189], v[214:217], v[80:83]
	v_mfma_f32_16x16x32_bf16 v[68:71], v[178:181], v[222:225], v[68:71]
	v_mfma_f32_16x16x32_bf16 v[64:67], v[186:189], v[222:225], v[64:67]
	s_barrier
	s_add_i32 s91, s81, s30
	s_add_u32 s98, s76, s34
	s_addc_u32 s99, s77, s35
	s_mov_b32 m0, s91
	ds_read_b128 v[190:193], v168 offset:16384
	ds_read_b128 v[194:197], v168 offset:17408
	ds_read_b128 v[198:201], v168 offset:18432
	ds_read_b128 v[202:205], v168 offset:19456
	ds_read_b128 v[206:209], v168 offset:20480
	ds_read_b128 v[214:217], v168 offset:21504
	ds_read_b128 v[218:221], v168 offset:22528
	ds_read_b128 v[222:225], v168 offset:23552
	global_load_lds_dwordx4 v130, s[76:77]
	s_add_i32 m0, s91, 0x2000
	s_add_u32 s92, s76, 0x80000
	s_addc_u32 s93, s77, 0
	s_add_i32 s91, s83, s30
	global_load_lds_dwordx4 v134, s[76:77]
	s_mov_b32 m0, s91
	s_add_u32 s100, s78, s34
	s_addc_u32 s101, s79, s35
	global_load_lds_dwordx4 v130, s[92:93]
	s_add_i32 m0, s91, 0x2000
	s_nop 0
	global_load_lds_dwordx4 v134, s[92:93]
	s_mov_b32 m0, s31
	s_nop 0
	global_load_lds_dwordx4 v128, s[78:79]
	s_mov_b32 m0, s51
	s_nop 0
	global_load_lds_dwordx4 v132, s[78:79]
	s_waitcnt vmcnt(8)
	s_waitcnt lgkmcnt(0)
	s_barrier
	v_mfma_f32_16x16x32_bf16 v[60:63], v[146:149], v[190:193], 0
	v_mfma_f32_16x16x32_bf16 v[56:59], v[154:157], v[190:193], 0
	v_mfma_f32_16x16x32_bf16 v[44:47], v[146:149], v[198:201], 0
	v_mfma_f32_16x16x32_bf16 v[40:43], v[154:157], v[198:201], 0
	v_mfma_f32_16x16x32_bf16 v[28:31], v[146:149], v[206:209], 0
	v_mfma_f32_16x16x32_bf16 v[24:27], v[154:157], v[206:209], 0
	v_mfma_f32_16x16x32_bf16 v[12:15], v[146:149], v[218:221], 0
	v_mfma_f32_16x16x32_bf16 v[8:11], v[154:157], v[218:221], 0
	v_mfma_f32_16x16x32_bf16 v[60:63], v[150:153], v[194:197], v[60:63]
	v_mfma_f32_16x16x32_bf16 v[56:59], v[170:173], v[194:197], v[56:59]
	v_mfma_f32_16x16x32_bf16 v[44:47], v[150:153], v[202:205], v[44:47]
	v_mfma_f32_16x16x32_bf16 v[40:43], v[170:173], v[202:205], v[40:43]
	v_mfma_f32_16x16x32_bf16 v[28:31], v[150:153], v[214:217], v[28:31]
	v_mfma_f32_16x16x32_bf16 v[24:27], v[170:173], v[214:217], v[24:27]
	v_mfma_f32_16x16x32_bf16 v[12:15], v[150:153], v[222:225], v[12:15]
	v_mfma_f32_16x16x32_bf16 v[8:11], v[170:173], v[222:225], v[8:11]
	v_mfma_f32_16x16x32_bf16 v[52:55], v[174:177], v[190:193], 0
	v_mfma_f32_16x16x32_bf16 v[48:51], v[182:185], v[190:193], 0
	v_mfma_f32_16x16x32_bf16 v[36:39], v[174:177], v[198:201], 0
	v_mfma_f32_16x16x32_bf16 v[32:35], v[182:185], v[198:201], 0
	v_mfma_f32_16x16x32_bf16 v[20:23], v[174:177], v[206:209], 0
	v_mfma_f32_16x16x32_bf16 v[16:19], v[182:185], v[206:209], 0
	v_mfma_f32_16x16x32_bf16 v[4:7], v[174:177], v[218:221], 0
	v_mfma_f32_16x16x32_bf16 v[0:3], v[182:185], v[218:221], 0
	v_mfma_f32_16x16x32_bf16 v[52:55], v[178:181], v[194:197], v[52:55]
	v_mfma_f32_16x16x32_bf16 v[48:51], v[186:189], v[194:197], v[48:51]
	v_mfma_f32_16x16x32_bf16 v[36:39], v[178:181], v[202:205], v[36:39]
	v_mfma_f32_16x16x32_bf16 v[32:35], v[186:189], v[202:205], v[32:35]
	v_mfma_f32_16x16x32_bf16 v[20:23], v[178:181], v[214:217], v[20:23]
	v_mfma_f32_16x16x32_bf16 v[16:19], v[186:189], v[214:217], v[16:19]
	v_mfma_f32_16x16x32_bf16 v[4:7], v[178:181], v[222:225], v[4:7]
	v_mfma_f32_16x16x32_bf16 v[0:3], v[186:189], v[222:225], v[0:3]
	s_barrier
	s_add_i32 s91, 0, 0x18000
	s_add_i32 s92, 0, 0x1c000
	ds_read_b128 v[146:149], v253
	ds_read_b128 v[150:153], v253 offset:1024
	ds_read_b128 v[154:157], v253 offset:2048
	ds_read_b128 v[170:173], v253 offset:3072
	ds_read_b128 v[174:177], v254
	ds_read_b128 v[178:181], v254 offset:1024
	ds_read_b128 v[182:185], v254 offset:2048
	ds_read_b128 v[186:189], v254 offset:3072
	s_add_u32 s78, s78, 0x80000
	s_addc_u32 s79, s79, 0
	s_mov_b32 m0, s28
	ds_read_b128 v[190:193], v168 offset:32768
	ds_read_b128 v[194:197], v168 offset:33792
	ds_read_b128 v[198:201], v168 offset:34816
	ds_read_b128 v[202:205], v168 offset:35840
	ds_read_b128 v[206:209], v168 offset:36864
	ds_read_b128 v[214:217], v168 offset:37888
	ds_read_b128 v[218:221], v168 offset:38912
	ds_read_b128 v[222:225], v168 offset:39936
	global_load_lds_dwordx4 v128, s[78:79]
	s_mov_b32 m0, s29
	s_nop 0
	global_load_lds_dwordx4 v132, s[78:79]
	s_waitcnt vmcnt(8)
	s_waitcnt lgkmcnt(0)
	s_barrier
	v_mfma_f32_16x16x32_bf16 v[124:127], v[146:149], v[190:193], v[124:127]
	v_mfma_f32_16x16x32_bf16 v[120:123], v[154:157], v[190:193], v[120:123]
	v_mfma_f32_16x16x32_bf16 v[108:111], v[146:149], v[198:201], v[108:111]
	v_mfma_f32_16x16x32_bf16 v[104:107], v[154:157], v[198:201], v[104:107]
	v_mfma_f32_16x16x32_bf16 v[92:95], v[146:149], v[206:209], v[92:95]
	v_mfma_f32_16x16x32_bf16 v[88:91], v[154:157], v[206:209], v[88:91]
	v_mfma_f32_16x16x32_bf16 v[76:79], v[146:149], v[218:221], v[76:79]
	v_mfma_f32_16x16x32_bf16 v[72:75], v[154:157], v[218:221], v[72:75]
	v_mfma_f32_16x16x32_bf16 v[124:127], v[150:153], v[194:197], v[124:127]
	v_mfma_f32_16x16x32_bf16 v[120:123], v[170:173], v[194:197], v[120:123]
	v_mfma_f32_16x16x32_bf16 v[108:111], v[150:153], v[202:205], v[108:111]
	v_mfma_f32_16x16x32_bf16 v[104:107], v[170:173], v[202:205], v[104:107]
	v_mfma_f32_16x16x32_bf16 v[92:95], v[150:153], v[214:217], v[92:95]
	v_mfma_f32_16x16x32_bf16 v[88:91], v[170:173], v[214:217], v[88:91]
	v_mfma_f32_16x16x32_bf16 v[76:79], v[150:153], v[222:225], v[76:79]
	v_mfma_f32_16x16x32_bf16 v[72:75], v[170:173], v[222:225], v[72:75]
	v_mfma_f32_16x16x32_bf16 v[116:119], v[174:177], v[190:193], v[116:119]
	v_mfma_f32_16x16x32_bf16 v[112:115], v[182:185], v[190:193], v[112:115]
	v_mfma_f32_16x16x32_bf16 v[100:103], v[174:177], v[198:201], v[100:103]
	v_mfma_f32_16x16x32_bf16 v[96:99], v[182:185], v[198:201], v[96:99]
	v_mfma_f32_16x16x32_bf16 v[84:87], v[174:177], v[206:209], v[84:87]
	v_mfma_f32_16x16x32_bf16 v[80:83], v[182:185], v[206:209], v[80:83]
	v_mfma_f32_16x16x32_bf16 v[68:71], v[174:177], v[218:221], v[68:71]
	v_mfma_f32_16x16x32_bf16 v[64:67], v[182:185], v[218:221], v[64:67]
	v_mfma_f32_16x16x32_bf16 v[116:119], v[178:181], v[194:197], v[116:119]
	v_mfma_f32_16x16x32_bf16 v[112:115], v[186:189], v[194:197], v[112:115]
	v_mfma_f32_16x16x32_bf16 v[100:103], v[178:181], v[202:205], v[100:103]
	v_mfma_f32_16x16x32_bf16 v[96:99], v[186:189], v[202:205], v[96:99]
	v_mfma_f32_16x16x32_bf16 v[84:87], v[178:181], v[214:217], v[84:87]
	v_mfma_f32_16x16x32_bf16 v[80:83], v[186:189], v[214:217], v[80:83]
	v_mfma_f32_16x16x32_bf16 v[68:71], v[178:181], v[222:225], v[68:71]
	v_mfma_f32_16x16x32_bf16 v[64:67], v[186:189], v[222:225], v[64:67]
	s_barrier
	s_add_i32 s78, s91, s30
	s_mov_b32 m0, s78
	ds_read_b128 v[190:193], v168 offset:49152
	ds_read_b128 v[194:197], v168 offset:50176
	ds_read_b128 v[198:201], v168 offset:51200
	ds_read_b128 v[202:205], v168 offset:52224
	ds_read_b128 v[206:209], v168 offset:53248
	ds_read_b128 v[214:217], v168 offset:54272
	ds_read_b128 v[218:221], v168 offset:55296
	ds_read_b128 v[222:225], v168 offset:56320
	global_load_lds_dwordx4 v130, s[98:99]
	s_add_i32 m0, s78, 0x2000
	s_add_u32 s76, s76, 0x80080
	s_addc_u32 s77, s77, 0
	s_add_i32 s78, s92, s30
	global_load_lds_dwordx4 v134, s[98:99]
	s_mov_b32 m0, s78
	s_nop 0
	global_load_lds_dwordx4 v130, s[76:77]
	s_add_i32 m0, s78, 0x2000
	s_nop 0
	global_load_lds_dwordx4 v134, s[76:77]
	s_mov_b32 m0, s73
	s_nop 0
	global_load_lds_dwordx4 v128, s[100:101]
	s_mov_b32 m0, s80
	s_nop 0
	global_load_lds_dwordx4 v132, s[100:101]
	s_waitcnt vmcnt(8)
	s_waitcnt lgkmcnt(0)
	s_barrier
	v_mfma_f32_16x16x32_bf16 v[60:63], v[146:149], v[190:193], v[60:63]
	v_mfma_f32_16x16x32_bf16 v[56:59], v[154:157], v[190:193], v[56:59]
	v_mfma_f32_16x16x32_bf16 v[44:47], v[146:149], v[198:201], v[44:47]
	v_mfma_f32_16x16x32_bf16 v[40:43], v[154:157], v[198:201], v[40:43]
	v_mfma_f32_16x16x32_bf16 v[28:31], v[146:149], v[206:209], v[28:31]
	v_mfma_f32_16x16x32_bf16 v[24:27], v[154:157], v[206:209], v[24:27]
	v_mfma_f32_16x16x32_bf16 v[12:15], v[146:149], v[218:221], v[12:15]
	v_mfma_f32_16x16x32_bf16 v[8:11], v[154:157], v[218:221], v[8:11]
	v_mfma_f32_16x16x32_bf16 v[60:63], v[150:153], v[194:197], v[60:63]
	v_mfma_f32_16x16x32_bf16 v[56:59], v[170:173], v[194:197], v[56:59]
	v_mfma_f32_16x16x32_bf16 v[44:47], v[150:153], v[202:205], v[44:47]
	v_mfma_f32_16x16x32_bf16 v[40:43], v[170:173], v[202:205], v[40:43]
	v_mfma_f32_16x16x32_bf16 v[28:31], v[150:153], v[214:217], v[28:31]
	v_mfma_f32_16x16x32_bf16 v[24:27], v[170:173], v[214:217], v[24:27]
	v_mfma_f32_16x16x32_bf16 v[12:15], v[150:153], v[222:225], v[12:15]
	v_mfma_f32_16x16x32_bf16 v[8:11], v[170:173], v[222:225], v[8:11]
	v_mfma_f32_16x16x32_bf16 v[52:55], v[174:177], v[190:193], v[52:55]
	v_mfma_f32_16x16x32_bf16 v[48:51], v[182:185], v[190:193], v[48:51]
	v_mfma_f32_16x16x32_bf16 v[36:39], v[174:177], v[198:201], v[36:39]
	v_mfma_f32_16x16x32_bf16 v[32:35], v[182:185], v[198:201], v[32:35]
	v_mfma_f32_16x16x32_bf16 v[20:23], v[174:177], v[206:209], v[20:23]
	v_mfma_f32_16x16x32_bf16 v[16:19], v[182:185], v[206:209], v[16:19]
	v_mfma_f32_16x16x32_bf16 v[4:7], v[174:177], v[218:221], v[4:7]
	v_mfma_f32_16x16x32_bf16 v[0:3], v[182:185], v[218:221], v[0:3]
	v_mfma_f32_16x16x32_bf16 v[52:55], v[178:181], v[194:197], v[52:55]
	v_mfma_f32_16x16x32_bf16 v[48:51], v[186:189], v[194:197], v[48:51]
	v_mfma_f32_16x16x32_bf16 v[36:39], v[178:181], v[202:205], v[36:39]
	v_mfma_f32_16x16x32_bf16 v[32:35], v[186:189], v[202:205], v[32:35]
	v_mfma_f32_16x16x32_bf16 v[20:23], v[178:181], v[214:217], v[20:23]
	v_mfma_f32_16x16x32_bf16 v[16:19], v[186:189], v[214:217], v[16:19]
	v_mfma_f32_16x16x32_bf16 v[4:7], v[178:181], v[222:225], v[4:7]
	v_mfma_f32_16x16x32_bf16 v[0:3], v[186:189], v[222:225], v[0:3]
	s_barrier
	s_add_i32 s90, s90, 2
	s_add_u32 s74, s74, 0x100
	s_addc_u32 s75, s75, 0
	s_add_u32 s65, s65, 0x100
	s_addc_u32 s71, s71, 0
	s_cmp_gt_u32 s90, 29
.LBB0_272:
	ds_read_b128 v[146:149], v166
	ds_read_b128 v[150:153], v166 offset:1024
	ds_read_b128 v[154:157], v166 offset:2048
	ds_read_b128 v[170:173], v166 offset:3072
	ds_read_b128 v[174:177], v167
	ds_read_b128 v[178:181], v167 offset:1024
	ds_read_b128 v[182:185], v167 offset:2048
	ds_read_b128 v[186:189], v167 offset:3072
	s_add_u32 s76, s74, 0xfff80080
	s_addc_u32 s77, s75, -1
	s_cmp_eq_u32 s90, 28
	s_cselect_b32 s79, s0, s77
	s_cselect_b32 s78, s1, s76
	s_cselect_b32 s77, s3, s71
	s_cselect_b32 s76, s63, s65
	s_add_i32 m0, s31, 0xc000
	ds_read_b128 v[190:193], v168
	ds_read_b128 v[194:197], v168 offset:1024
	ds_read_b128 v[198:201], v168 offset:2048
	ds_read_b128 v[202:205], v168 offset:3072
	ds_read_b128 v[206:209], v168 offset:4096
	ds_read_b128 v[214:217], v168 offset:5120
	ds_read_b128 v[218:221], v168 offset:6144
	ds_read_b128 v[222:225], v168 offset:7168
	global_load_lds_dwordx4 v138, s[74:75]
	s_add_i32 m0, s31, 0xe000
	s_nop 0
	global_load_lds_dwordx4 v140, s[74:75]
	s_waitcnt vmcnt(8)
	s_waitcnt lgkmcnt(0)
	s_barrier
	v_mfma_f32_16x16x32_bf16 v[124:127], v[146:149], v[190:193], v[124:127]
	v_mfma_f32_16x16x32_bf16 v[120:123], v[154:157], v[190:193], v[120:123]
	v_mfma_f32_16x16x32_bf16 v[108:111], v[146:149], v[198:201], v[108:111]
	v_mfma_f32_16x16x32_bf16 v[104:107], v[154:157], v[198:201], v[104:107]
	v_mfma_f32_16x16x32_bf16 v[92:95], v[146:149], v[206:209], v[92:95]
	v_mfma_f32_16x16x32_bf16 v[88:91], v[154:157], v[206:209], v[88:91]
	v_mfma_f32_16x16x32_bf16 v[76:79], v[146:149], v[218:221], v[76:79]
	v_mfma_f32_16x16x32_bf16 v[72:75], v[154:157], v[218:221], v[72:75]
	v_mfma_f32_16x16x32_bf16 v[124:127], v[150:153], v[194:197], v[124:127]
	v_mfma_f32_16x16x32_bf16 v[120:123], v[170:173], v[194:197], v[120:123]
	v_mfma_f32_16x16x32_bf16 v[108:111], v[150:153], v[202:205], v[108:111]
	v_mfma_f32_16x16x32_bf16 v[104:107], v[170:173], v[202:205], v[104:107]
	v_mfma_f32_16x16x32_bf16 v[92:95], v[150:153], v[214:217], v[92:95]
	v_mfma_f32_16x16x32_bf16 v[88:91], v[170:173], v[214:217], v[88:91]
	v_mfma_f32_16x16x32_bf16 v[76:79], v[150:153], v[222:225], v[76:79]
	v_mfma_f32_16x16x32_bf16 v[72:75], v[170:173], v[222:225], v[72:75]
	v_mfma_f32_16x16x32_bf16 v[116:119], v[174:177], v[190:193], v[116:119]
	v_mfma_f32_16x16x32_bf16 v[112:115], v[182:185], v[190:193], v[112:115]
	v_mfma_f32_16x16x32_bf16 v[100:103], v[174:177], v[198:201], v[100:103]
	v_mfma_f32_16x16x32_bf16 v[96:99], v[182:185], v[198:201], v[96:99]
	v_mfma_f32_16x16x32_bf16 v[84:87], v[174:177], v[206:209], v[84:87]
	v_mfma_f32_16x16x32_bf16 v[80:83], v[182:185], v[206:209], v[80:83]
	v_mfma_f32_16x16x32_bf16 v[68:71], v[174:177], v[218:221], v[68:71]
	v_mfma_f32_16x16x32_bf16 v[64:67], v[182:185], v[218:221], v[64:67]
	v_mfma_f32_16x16x32_bf16 v[116:119], v[178:181], v[194:197], v[116:119]
	v_mfma_f32_16x16x32_bf16 v[112:115], v[186:189], v[194:197], v[112:115]
	v_mfma_f32_16x16x32_bf16 v[100:103], v[178:181], v[202:205], v[100:103]
	v_mfma_f32_16x16x32_bf16 v[96:99], v[186:189], v[202:205], v[96:99]
	v_mfma_f32_16x16x32_bf16 v[84:87], v[178:181], v[214:217], v[84:87]
	v_mfma_f32_16x16x32_bf16 v[80:83], v[186:189], v[214:217], v[80:83]
	v_mfma_f32_16x16x32_bf16 v[68:71], v[178:181], v[222:225], v[68:71]
	v_mfma_f32_16x16x32_bf16 v[64:67], v[186:189], v[222:225], v[64:67]
	s_barrier
	s_add_i32 s91, s81, s30
	s_add_u32 s98, s76, s34
	s_addc_u32 s99, s77, s35
	s_mov_b32 m0, s91
	ds_read_b128 v[190:193], v168 offset:16384
	ds_read_b128 v[194:197], v168 offset:17408
	ds_read_b128 v[198:201], v168 offset:18432
	ds_read_b128 v[202:205], v168 offset:19456
	ds_read_b128 v[206:209], v168 offset:20480
	ds_read_b128 v[214:217], v168 offset:21504
	ds_read_b128 v[218:221], v168 offset:22528
	ds_read_b128 v[222:225], v168 offset:23552
	global_load_lds_dwordx4 v130, s[76:77]
	s_add_i32 m0, s91, 0x2000
	s_add_u32 s92, s76, 0x80000
	s_addc_u32 s93, s77, 0
	s_add_i32 s91, s83, s30
	global_load_lds_dwordx4 v134, s[76:77]
	s_mov_b32 m0, s91
	s_add_u32 s100, s78, s34
	s_addc_u32 s101, s79, s35
	global_load_lds_dwordx4 v130, s[92:93]
	s_add_i32 m0, s91, 0x2000
	s_nop 0
	global_load_lds_dwordx4 v134, s[92:93]
	s_mov_b32 m0, s31
	s_nop 0
	global_load_lds_dwordx4 v128, s[78:79]
	s_mov_b32 m0, s51
	s_nop 0
	global_load_lds_dwordx4 v132, s[78:79]
	s_waitcnt vmcnt(8)
	s_waitcnt lgkmcnt(0)
	s_barrier
	v_mfma_f32_16x16x32_bf16 v[60:63], v[146:149], v[190:193], v[60:63]
	v_mfma_f32_16x16x32_bf16 v[56:59], v[154:157], v[190:193], v[56:59]
	v_mfma_f32_16x16x32_bf16 v[44:47], v[146:149], v[198:201], v[44:47]
	v_mfma_f32_16x16x32_bf16 v[40:43], v[154:157], v[198:201], v[40:43]
	v_mfma_f32_16x16x32_bf16 v[28:31], v[146:149], v[206:209], v[28:31]
	v_mfma_f32_16x16x32_bf16 v[24:27], v[154:157], v[206:209], v[24:27]
	v_mfma_f32_16x16x32_bf16 v[12:15], v[146:149], v[218:221], v[12:15]
	v_mfma_f32_16x16x32_bf16 v[8:11], v[154:157], v[218:221], v[8:11]
	v_mfma_f32_16x16x32_bf16 v[60:63], v[150:153], v[194:197], v[60:63]
	v_mfma_f32_16x16x32_bf16 v[56:59], v[170:173], v[194:197], v[56:59]
	v_mfma_f32_16x16x32_bf16 v[44:47], v[150:153], v[202:205], v[44:47]
	v_mfma_f32_16x16x32_bf16 v[40:43], v[170:173], v[202:205], v[40:43]
	v_mfma_f32_16x16x32_bf16 v[28:31], v[150:153], v[214:217], v[28:31]
	v_mfma_f32_16x16x32_bf16 v[24:27], v[170:173], v[214:217], v[24:27]
	v_mfma_f32_16x16x32_bf16 v[12:15], v[150:153], v[222:225], v[12:15]
	v_mfma_f32_16x16x32_bf16 v[8:11], v[170:173], v[222:225], v[8:11]
	v_mfma_f32_16x16x32_bf16 v[52:55], v[174:177], v[190:193], v[52:55]
	v_mfma_f32_16x16x32_bf16 v[48:51], v[182:185], v[190:193], v[48:51]
	v_mfma_f32_16x16x32_bf16 v[36:39], v[174:177], v[198:201], v[36:39]
	v_mfma_f32_16x16x32_bf16 v[32:35], v[182:185], v[198:201], v[32:35]
	v_mfma_f32_16x16x32_bf16 v[20:23], v[174:177], v[206:209], v[20:23]
	v_mfma_f32_16x16x32_bf16 v[16:19], v[182:185], v[206:209], v[16:19]
	v_mfma_f32_16x16x32_bf16 v[4:7], v[174:177], v[218:221], v[4:7]
	v_mfma_f32_16x16x32_bf16 v[0:3], v[182:185], v[218:221], v[0:3]
	v_mfma_f32_16x16x32_bf16 v[52:55], v[178:181], v[194:197], v[52:55]
	v_mfma_f32_16x16x32_bf16 v[48:51], v[186:189], v[194:197], v[48:51]
	v_mfma_f32_16x16x32_bf16 v[36:39], v[178:181], v[202:205], v[36:39]
	v_mfma_f32_16x16x32_bf16 v[32:35], v[186:189], v[202:205], v[32:35]
	v_mfma_f32_16x16x32_bf16 v[20:23], v[178:181], v[214:217], v[20:23]
	v_mfma_f32_16x16x32_bf16 v[16:19], v[186:189], v[214:217], v[16:19]
	v_mfma_f32_16x16x32_bf16 v[4:7], v[178:181], v[222:225], v[4:7]
	v_mfma_f32_16x16x32_bf16 v[0:3], v[186:189], v[222:225], v[0:3]
	s_barrier
	s_add_i32 s91, 0, 0x18000
	s_add_i32 s92, 0, 0x1c000
	ds_read_b128 v[146:149], v253
	ds_read_b128 v[150:153], v253 offset:1024
	ds_read_b128 v[154:157], v253 offset:2048
	ds_read_b128 v[170:173], v253 offset:3072
	ds_read_b128 v[174:177], v254
	ds_read_b128 v[178:181], v254 offset:1024
	ds_read_b128 v[182:185], v254 offset:2048
	ds_read_b128 v[186:189], v254 offset:3072
	s_add_u32 s78, s78, 0x80000
	s_addc_u32 s79, s79, 0
	s_mov_b32 m0, s28
	ds_read_b128 v[190:193], v168 offset:32768
	ds_read_b128 v[194:197], v168 offset:33792
	ds_read_b128 v[198:201], v168 offset:34816
	ds_read_b128 v[202:205], v168 offset:35840
	ds_read_b128 v[206:209], v168 offset:36864
	ds_read_b128 v[214:217], v168 offset:37888
	ds_read_b128 v[218:221], v168 offset:38912
	ds_read_b128 v[222:225], v168 offset:39936
	global_load_lds_dwordx4 v128, s[78:79]
	s_mov_b32 m0, s29
	s_nop 0
	global_load_lds_dwordx4 v132, s[78:79]
	s_waitcnt vmcnt(8)
	s_waitcnt lgkmcnt(0)
	s_barrier
	v_mfma_f32_16x16x32_bf16 v[124:127], v[146:149], v[190:193], v[124:127]
	v_mfma_f32_16x16x32_bf16 v[120:123], v[154:157], v[190:193], v[120:123]
	v_mfma_f32_16x16x32_bf16 v[108:111], v[146:149], v[198:201], v[108:111]
	v_mfma_f32_16x16x32_bf16 v[104:107], v[154:157], v[198:201], v[104:107]
	v_mfma_f32_16x16x32_bf16 v[92:95], v[146:149], v[206:209], v[92:95]
	v_mfma_f32_16x16x32_bf16 v[88:91], v[154:157], v[206:209], v[88:91]
	v_mfma_f32_16x16x32_bf16 v[76:79], v[146:149], v[218:221], v[76:79]
	v_mfma_f32_16x16x32_bf16 v[72:75], v[154:157], v[218:221], v[72:75]
	v_mfma_f32_16x16x32_bf16 v[124:127], v[150:153], v[194:197], v[124:127]
	v_mfma_f32_16x16x32_bf16 v[120:123], v[170:173], v[194:197], v[120:123]
	v_mfma_f32_16x16x32_bf16 v[108:111], v[150:153], v[202:205], v[108:111]
	v_mfma_f32_16x16x32_bf16 v[104:107], v[170:173], v[202:205], v[104:107]
	v_mfma_f32_16x16x32_bf16 v[92:95], v[150:153], v[214:217], v[92:95]
	v_mfma_f32_16x16x32_bf16 v[88:91], v[170:173], v[214:217], v[88:91]
	v_mfma_f32_16x16x32_bf16 v[76:79], v[150:153], v[222:225], v[76:79]
	v_mfma_f32_16x16x32_bf16 v[72:75], v[170:173], v[222:225], v[72:75]
	v_mfma_f32_16x16x32_bf16 v[116:119], v[174:177], v[190:193], v[116:119]
	v_mfma_f32_16x16x32_bf16 v[112:115], v[182:185], v[190:193], v[112:115]
	v_mfma_f32_16x16x32_bf16 v[100:103], v[174:177], v[198:201], v[100:103]
	v_mfma_f32_16x16x32_bf16 v[96:99], v[182:185], v[198:201], v[96:99]
	v_mfma_f32_16x16x32_bf16 v[84:87], v[174:177], v[206:209], v[84:87]
	v_mfma_f32_16x16x32_bf16 v[80:83], v[182:185], v[206:209], v[80:83]
	v_mfma_f32_16x16x32_bf16 v[68:71], v[174:177], v[218:221], v[68:71]
	v_mfma_f32_16x16x32_bf16 v[64:67], v[182:185], v[218:221], v[64:67]
	v_mfma_f32_16x16x32_bf16 v[116:119], v[178:181], v[194:197], v[116:119]
	v_mfma_f32_16x16x32_bf16 v[112:115], v[186:189], v[194:197], v[112:115]
	v_mfma_f32_16x16x32_bf16 v[100:103], v[178:181], v[202:205], v[100:103]
	v_mfma_f32_16x16x32_bf16 v[96:99], v[186:189], v[202:205], v[96:99]
	v_mfma_f32_16x16x32_bf16 v[84:87], v[178:181], v[214:217], v[84:87]
	v_mfma_f32_16x16x32_bf16 v[80:83], v[186:189], v[214:217], v[80:83]
	v_mfma_f32_16x16x32_bf16 v[68:71], v[178:181], v[222:225], v[68:71]
	v_mfma_f32_16x16x32_bf16 v[64:67], v[186:189], v[222:225], v[64:67]
	s_barrier
	s_add_i32 s78, s91, s30
	s_mov_b32 m0, s78
	ds_read_b128 v[190:193], v168 offset:49152
	ds_read_b128 v[194:197], v168 offset:50176
	ds_read_b128 v[198:201], v168 offset:51200
	ds_read_b128 v[202:205], v168 offset:52224
	ds_read_b128 v[206:209], v168 offset:53248
	ds_read_b128 v[214:217], v168 offset:54272
	ds_read_b128 v[218:221], v168 offset:55296
	ds_read_b128 v[222:225], v168 offset:56320
	global_load_lds_dwordx4 v130, s[98:99]
	s_add_i32 m0, s78, 0x2000
	s_add_u32 s76, s76, 0x80080
	s_addc_u32 s77, s77, 0
	s_add_i32 s78, s92, s30
	global_load_lds_dwordx4 v134, s[98:99]
	s_mov_b32 m0, s78
	s_nop 0
	global_load_lds_dwordx4 v130, s[76:77]
	s_add_i32 m0, s78, 0x2000
	s_nop 0
	global_load_lds_dwordx4 v134, s[76:77]
	s_mov_b32 m0, s73
	s_nop 0
	global_load_lds_dwordx4 v128, s[100:101]
	s_mov_b32 m0, s80
	s_nop 0
	global_load_lds_dwordx4 v132, s[100:101]
	s_waitcnt vmcnt(8)
	s_waitcnt lgkmcnt(0)
	s_barrier
	v_mfma_f32_16x16x32_bf16 v[60:63], v[146:149], v[190:193], v[60:63]
	v_mfma_f32_16x16x32_bf16 v[56:59], v[154:157], v[190:193], v[56:59]
	v_mfma_f32_16x16x32_bf16 v[44:47], v[146:149], v[198:201], v[44:47]
	v_mfma_f32_16x16x32_bf16 v[40:43], v[154:157], v[198:201], v[40:43]
	v_mfma_f32_16x16x32_bf16 v[28:31], v[146:149], v[206:209], v[28:31]
	v_mfma_f32_16x16x32_bf16 v[24:27], v[154:157], v[206:209], v[24:27]
	v_mfma_f32_16x16x32_bf16 v[12:15], v[146:149], v[218:221], v[12:15]
	v_mfma_f32_16x16x32_bf16 v[8:11], v[154:157], v[218:221], v[8:11]
	v_mfma_f32_16x16x32_bf16 v[60:63], v[150:153], v[194:197], v[60:63]
	v_mfma_f32_16x16x32_bf16 v[56:59], v[170:173], v[194:197], v[56:59]
	v_mfma_f32_16x16x32_bf16 v[44:47], v[150:153], v[202:205], v[44:47]
	v_mfma_f32_16x16x32_bf16 v[40:43], v[170:173], v[202:205], v[40:43]
	v_mfma_f32_16x16x32_bf16 v[28:31], v[150:153], v[214:217], v[28:31]
	v_mfma_f32_16x16x32_bf16 v[24:27], v[170:173], v[214:217], v[24:27]
	v_mfma_f32_16x16x32_bf16 v[12:15], v[150:153], v[222:225], v[12:15]
	v_mfma_f32_16x16x32_bf16 v[8:11], v[170:173], v[222:225], v[8:11]
	v_mfma_f32_16x16x32_bf16 v[52:55], v[174:177], v[190:193], v[52:55]
	v_mfma_f32_16x16x32_bf16 v[48:51], v[182:185], v[190:193], v[48:51]
	v_mfma_f32_16x16x32_bf16 v[36:39], v[174:177], v[198:201], v[36:39]
	v_mfma_f32_16x16x32_bf16 v[32:35], v[182:185], v[198:201], v[32:35]
	v_mfma_f32_16x16x32_bf16 v[20:23], v[174:177], v[206:209], v[20:23]
	v_mfma_f32_16x16x32_bf16 v[16:19], v[182:185], v[206:209], v[16:19]
	v_mfma_f32_16x16x32_bf16 v[4:7], v[174:177], v[218:221], v[4:7]
	v_mfma_f32_16x16x32_bf16 v[0:3], v[182:185], v[218:221], v[0:3]
	v_mfma_f32_16x16x32_bf16 v[52:55], v[178:181], v[194:197], v[52:55]
	v_mfma_f32_16x16x32_bf16 v[48:51], v[186:189], v[194:197], v[48:51]
	v_mfma_f32_16x16x32_bf16 v[36:39], v[178:181], v[202:205], v[36:39]
	v_mfma_f32_16x16x32_bf16 v[32:35], v[186:189], v[202:205], v[32:35]
	v_mfma_f32_16x16x32_bf16 v[20:23], v[178:181], v[214:217], v[20:23]
	v_mfma_f32_16x16x32_bf16 v[16:19], v[186:189], v[214:217], v[16:19]
	v_mfma_f32_16x16x32_bf16 v[4:7], v[178:181], v[222:225], v[4:7]
	v_mfma_f32_16x16x32_bf16 v[0:3], v[186:189], v[222:225], v[0:3]
	s_barrier
	s_add_i32 s90, s90, 2
	s_add_u32 s74, s74, 0x100
	s_addc_u32 s75, s75, 0
	s_add_u32 s65, s65, 0x100
	s_addc_u32 s71, s71, 0
	s_cmp_gt_u32 s90, 29
	s_cbranch_scc0 .LBB0_272
	s_setprio 0
	s_and_b64 vcc, exec, s[36:37]
	s_cbranch_vccz .LBB0_275
	s_barrier

.Lkprio_1:
	ds_read_b128 v[128:131], v216
	ds_read_b128 v[132:135], v216 offset:1024
	ds_read_b128 v[136:139], v216 offset:2048
	ds_read_b128 v[140:143], v216 offset:3072
	ds_read_b128 v[144:147], v217
	ds_read_b128 v[148:151], v217 offset:1024
	ds_read_b128 v[152:155], v217 offset:2048
	ds_read_b128 v[156:159], v217 offset:3072
	s_add_u32 s44, s42, 0xfff80080
	s_addc_u32 s45, s43, -1
	s_cmp_eq_u32 s58, 28
	s_cselect_b32 s47, s0, s45
	s_cselect_b32 s46, s1, s44
	s_cselect_b32 s45, s3, s35
	s_cselect_b32 s44, s9, s25
	s_add_i32 m0, s41, 0xc000
	ds_read_b128 v[160:163], v218
	ds_read_b128 v[164:167], v218 offset:1024
	ds_read_b128 v[168:171], v218 offset:2048
	ds_read_b128 v[172:175], v218 offset:3072
	ds_read_b128 v[192:195], v218 offset:4096
	ds_read_b128 v[196:199], v218 offset:5120
	ds_read_b128 v[200:203], v218 offset:6144
	ds_read_b128 v[204:207], v218 offset:7168
	global_load_lds_dwordx4 v184, s[42:43]
	s_add_i32 m0, s41, 0xe000
	s_nop 0
	global_load_lds_dwordx4 v186, s[42:43]
	s_waitcnt vmcnt(8)
	s_waitcnt lgkmcnt(0)
	s_barrier
	v_mfma_f32_16x16x32_bf16 v[124:127], v[128:131], v[160:163], 0
	v_mfma_f32_16x16x32_bf16 v[120:123], v[136:139], v[160:163], 0
	v_mfma_f32_16x16x32_bf16 v[108:111], v[128:131], v[168:171], 0
	v_mfma_f32_16x16x32_bf16 v[104:107], v[136:139], v[168:171], 0
	v_mfma_f32_16x16x32_bf16 v[92:95], v[128:131], v[192:195], 0
	v_mfma_f32_16x16x32_bf16 v[88:91], v[136:139], v[192:195], 0
	v_mfma_f32_16x16x32_bf16 v[76:79], v[128:131], v[200:203], 0
	v_mfma_f32_16x16x32_bf16 v[72:75], v[136:139], v[200:203], 0
	v_mfma_f32_16x16x32_bf16 v[124:127], v[132:135], v[164:167], v[124:127]
	v_mfma_f32_16x16x32_bf16 v[120:123], v[140:143], v[164:167], v[120:123]
	v_mfma_f32_16x16x32_bf16 v[108:111], v[132:135], v[172:175], v[108:111]
	v_mfma_f32_16x16x32_bf16 v[104:107], v[140:143], v[172:175], v[104:107]
	v_mfma_f32_16x16x32_bf16 v[92:95], v[132:135], v[196:199], v[92:95]
	v_mfma_f32_16x16x32_bf16 v[88:91], v[140:143], v[196:199], v[88:91]
	v_mfma_f32_16x16x32_bf16 v[76:79], v[132:135], v[204:207], v[76:79]
	v_mfma_f32_16x16x32_bf16 v[72:75], v[140:143], v[204:207], v[72:75]
	v_mfma_f32_16x16x32_bf16 v[116:119], v[144:147], v[160:163], 0
	v_mfma_f32_16x16x32_bf16 v[112:115], v[152:155], v[160:163], 0
	v_mfma_f32_16x16x32_bf16 v[100:103], v[144:147], v[168:171], 0
	v_mfma_f32_16x16x32_bf16 v[96:99], v[152:155], v[168:171], 0
	v_mfma_f32_16x16x32_bf16 v[84:87], v[144:147], v[192:195], 0
	v_mfma_f32_16x16x32_bf16 v[80:83], v[152:155], v[192:195], 0
	v_mfma_f32_16x16x32_bf16 v[68:71], v[144:147], v[200:203], 0
	v_mfma_f32_16x16x32_bf16 v[64:67], v[152:155], v[200:203], 0
	v_mfma_f32_16x16x32_bf16 v[116:119], v[148:151], v[164:167], v[116:119]
	v_mfma_f32_16x16x32_bf16 v[112:115], v[156:159], v[164:167], v[112:115]
	v_mfma_f32_16x16x32_bf16 v[100:103], v[148:151], v[172:175], v[100:103]
	v_mfma_f32_16x16x32_bf16 v[96:99], v[156:159], v[172:175], v[96:99]
	v_mfma_f32_16x16x32_bf16 v[84:87], v[148:151], v[196:199], v[84:87]
	v_mfma_f32_16x16x32_bf16 v[80:83], v[156:159], v[196:199], v[80:83]
	v_mfma_f32_16x16x32_bf16 v[68:71], v[148:151], v[204:207], v[68:71]
	v_mfma_f32_16x16x32_bf16 v[64:67], v[156:159], v[204:207], v[64:67]
	s_barrier
	s_add_i32 s59, s55, s31
	s_add_u32 s98, s44, s20
	s_addc_u32 s99, s45, s21
	s_mov_b32 m0, s59
	ds_read_b128 v[160:163], v218 offset:16384
	ds_read_b128 v[164:167], v218 offset:17408
	ds_read_b128 v[168:171], v218 offset:18432
	ds_read_b128 v[172:175], v218 offset:19456
	ds_read_b128 v[192:195], v218 offset:20480
	ds_read_b128 v[196:199], v218 offset:21504
	ds_read_b128 v[200:203], v218 offset:22528
	ds_read_b128 v[204:207], v218 offset:23552
	global_load_lds_dwordx4 v178, s[44:45]
	s_add_i32 m0, s59, 0x2000
	s_add_u32 s60, s44, 0x80000
	s_addc_u32 s61, s45, 0
	s_add_i32 s59, s56, s31
	global_load_lds_dwordx4 v182, s[44:45]
	s_mov_b32 m0, s59
	s_add_u32 s100, s46, s20
	s_addc_u32 s101, s47, s21
	global_load_lds_dwordx4 v178, s[60:61]
	s_add_i32 m0, s59, 0x2000
	s_nop 0
	global_load_lds_dwordx4 v182, s[60:61]
	s_mov_b32 m0, s41
	s_nop 0
	global_load_lds_dwordx4 v176, s[46:47]
	s_mov_b32 m0, s48
	s_nop 0
	global_load_lds_dwordx4 v180, s[46:47]
	s_waitcnt vmcnt(8)
	s_waitcnt lgkmcnt(0)
	s_barrier
	v_mfma_f32_16x16x32_bf16 v[60:63], v[128:131], v[160:163], 0
	v_mfma_f32_16x16x32_bf16 v[56:59], v[136:139], v[160:163], 0
	v_mfma_f32_16x16x32_bf16 v[44:47], v[128:131], v[168:171], 0
	v_mfma_f32_16x16x32_bf16 v[40:43], v[136:139], v[168:171], 0
	v_mfma_f32_16x16x32_bf16 v[28:31], v[128:131], v[192:195], 0
	v_mfma_f32_16x16x32_bf16 v[24:27], v[136:139], v[192:195], 0
	v_mfma_f32_16x16x32_bf16 v[12:15], v[128:131], v[200:203], 0
	v_mfma_f32_16x16x32_bf16 v[8:11], v[136:139], v[200:203], 0
	v_mfma_f32_16x16x32_bf16 v[60:63], v[132:135], v[164:167], v[60:63]
	v_mfma_f32_16x16x32_bf16 v[56:59], v[140:143], v[164:167], v[56:59]
	v_mfma_f32_16x16x32_bf16 v[44:47], v[132:135], v[172:175], v[44:47]
	v_mfma_f32_16x16x32_bf16 v[40:43], v[140:143], v[172:175], v[40:43]
	v_mfma_f32_16x16x32_bf16 v[28:31], v[132:135], v[196:199], v[28:31]
	v_mfma_f32_16x16x32_bf16 v[24:27], v[140:143], v[196:199], v[24:27]
	v_mfma_f32_16x16x32_bf16 v[12:15], v[132:135], v[204:207], v[12:15]
	v_mfma_f32_16x16x32_bf16 v[8:11], v[140:143], v[204:207], v[8:11]
	v_mfma_f32_16x16x32_bf16 v[52:55], v[144:147], v[160:163], 0
	v_mfma_f32_16x16x32_bf16 v[48:51], v[152:155], v[160:163], 0
	v_mfma_f32_16x16x32_bf16 v[36:39], v[144:147], v[168:171], 0
	v_mfma_f32_16x16x32_bf16 v[32:35], v[152:155], v[168:171], 0
	v_mfma_f32_16x16x32_bf16 v[20:23], v[144:147], v[192:195], 0
	v_mfma_f32_16x16x32_bf16 v[16:19], v[152:155], v[192:195], 0
	v_mfma_f32_16x16x32_bf16 v[4:7], v[144:147], v[200:203], 0
	v_mfma_f32_16x16x32_bf16 v[0:3], v[152:155], v[200:203], 0
	v_mfma_f32_16x16x32_bf16 v[52:55], v[148:151], v[164:167], v[52:55]
	v_mfma_f32_16x16x32_bf16 v[48:51], v[156:159], v[164:167], v[48:51]
	v_mfma_f32_16x16x32_bf16 v[36:39], v[148:151], v[172:175], v[36:39]
	v_mfma_f32_16x16x32_bf16 v[32:35], v[156:159], v[172:175], v[32:35]
	v_mfma_f32_16x16x32_bf16 v[20:23], v[148:151], v[196:199], v[20:23]
	v_mfma_f32_16x16x32_bf16 v[16:19], v[156:159], v[196:199], v[16:19]
	v_mfma_f32_16x16x32_bf16 v[4:7], v[148:151], v[204:207], v[4:7]
	v_mfma_f32_16x16x32_bf16 v[0:3], v[156:159], v[204:207], v[0:3]
	s_barrier
	s_add_i32 s59, 0, 0x18000
	s_add_i32 s60, 0, 0x1c000
	ds_read_b128 v[128:131], v253
	ds_read_b128 v[132:135], v253 offset:1024
	ds_read_b128 v[136:139], v253 offset:2048
	ds_read_b128 v[140:143], v253 offset:3072
	ds_read_b128 v[144:147], v254
	ds_read_b128 v[148:151], v254 offset:1024
	ds_read_b128 v[152:155], v254 offset:2048
	ds_read_b128 v[156:159], v254 offset:3072
	s_add_u32 s46, s46, 0x80000
	s_addc_u32 s47, s47, 0
	s_mov_b32 m0, s49
	ds_read_b128 v[160:163], v218 offset:32768
	ds_read_b128 v[164:167], v218 offset:33792
	ds_read_b128 v[168:171], v218 offset:34816
	ds_read_b128 v[172:175], v218 offset:35840
	ds_read_b128 v[192:195], v218 offset:36864
	ds_read_b128 v[196:199], v218 offset:37888
	ds_read_b128 v[200:203], v218 offset:38912
	ds_read_b128 v[204:207], v218 offset:39936
	global_load_lds_dwordx4 v176, s[46:47]
	s_mov_b32 m0, s50
	s_nop 0
	global_load_lds_dwordx4 v180, s[46:47]
	s_waitcnt vmcnt(8)
	s_waitcnt lgkmcnt(0)
	s_barrier
	v_mfma_f32_16x16x32_bf16 v[124:127], v[128:131], v[160:163], v[124:127]
	v_mfma_f32_16x16x32_bf16 v[120:123], v[136:139], v[160:163], v[120:123]
	v_mfma_f32_16x16x32_bf16 v[108:111], v[128:131], v[168:171], v[108:111]
	v_mfma_f32_16x16x32_bf16 v[104:107], v[136:139], v[168:171], v[104:107]
	v_mfma_f32_16x16x32_bf16 v[92:95], v[128:131], v[192:195], v[92:95]
	v_mfma_f32_16x16x32_bf16 v[88:91], v[136:139], v[192:195], v[88:91]
	v_mfma_f32_16x16x32_bf16 v[76:79], v[128:131], v[200:203], v[76:79]
	v_mfma_f32_16x16x32_bf16 v[72:75], v[136:139], v[200:203], v[72:75]
	v_mfma_f32_16x16x32_bf16 v[124:127], v[132:135], v[164:167], v[124:127]
	v_mfma_f32_16x16x32_bf16 v[120:123], v[140:143], v[164:167], v[120:123]
	v_mfma_f32_16x16x32_bf16 v[108:111], v[132:135], v[172:175], v[108:111]
	v_mfma_f32_16x16x32_bf16 v[104:107], v[140:143], v[172:175], v[104:107]
	v_mfma_f32_16x16x32_bf16 v[92:95], v[132:135], v[196:199], v[92:95]
	v_mfma_f32_16x16x32_bf16 v[88:91], v[140:143], v[196:199], v[88:91]
	v_mfma_f32_16x16x32_bf16 v[76:79], v[132:135], v[204:207], v[76:79]
	v_mfma_f32_16x16x32_bf16 v[72:75], v[140:143], v[204:207], v[72:75]
	v_mfma_f32_16x16x32_bf16 v[116:119], v[144:147], v[160:163], v[116:119]
	v_mfma_f32_16x16x32_bf16 v[112:115], v[152:155], v[160:163], v[112:115]
	v_mfma_f32_16x16x32_bf16 v[100:103], v[144:147], v[168:171], v[100:103]
	v_mfma_f32_16x16x32_bf16 v[96:99], v[152:155], v[168:171], v[96:99]
	v_mfma_f32_16x16x32_bf16 v[84:87], v[144:147], v[192:195], v[84:87]
	v_mfma_f32_16x16x32_bf16 v[80:83], v[152:155], v[192:195], v[80:83]
	v_mfma_f32_16x16x32_bf16 v[68:71], v[144:147], v[200:203], v[68:71]
	v_mfma_f32_16x16x32_bf16 v[64:67], v[152:155], v[200:203], v[64:67]
	v_mfma_f32_16x16x32_bf16 v[116:119], v[148:151], v[164:167], v[116:119]
	v_mfma_f32_16x16x32_bf16 v[112:115], v[156:159], v[164:167], v[112:115]
	v_mfma_f32_16x16x32_bf16 v[100:103], v[148:151], v[172:175], v[100:103]
	v_mfma_f32_16x16x32_bf16 v[96:99], v[156:159], v[172:175], v[96:99]
	v_mfma_f32_16x16x32_bf16 v[84:87], v[148:151], v[196:199], v[84:87]
	v_mfma_f32_16x16x32_bf16 v[80:83], v[156:159], v[196:199], v[80:83]
	v_mfma_f32_16x16x32_bf16 v[68:71], v[148:151], v[204:207], v[68:71]
	v_mfma_f32_16x16x32_bf16 v[64:67], v[156:159], v[204:207], v[64:67]
	s_barrier
	s_add_i32 s46, s59, s31
	s_mov_b32 m0, s46
	ds_read_b128 v[160:163], v218 offset:49152
	ds_read_b128 v[164:167], v218 offset:50176
	ds_read_b128 v[168:171], v218 offset:51200
	ds_read_b128 v[172:175], v218 offset:52224
	ds_read_b128 v[192:195], v218 offset:53248
	ds_read_b128 v[196:199], v218 offset:54272
	ds_read_b128 v[200:203], v218 offset:55296
	ds_read_b128 v[204:207], v218 offset:56320
	global_load_lds_dwordx4 v178, s[98:99]
	s_add_i32 m0, s46, 0x2000
	s_add_u32 s44, s44, 0x80080
	s_addc_u32 s45, s45, 0
	s_add_i32 s46, s60, s31
	global_load_lds_dwordx4 v182, s[98:99]
	s_mov_b32 m0, s46
	s_nop 0
	global_load_lds_dwordx4 v178, s[44:45]
	s_add_i32 m0, s46, 0x2000
	s_nop 0
	global_load_lds_dwordx4 v182, s[44:45]
	s_mov_b32 m0, s52
	s_nop 0
	global_load_lds_dwordx4 v176, s[100:101]
	s_mov_b32 m0, s53
	s_nop 0
	global_load_lds_dwordx4 v180, s[100:101]
	s_waitcnt vmcnt(8)
	s_waitcnt lgkmcnt(0)
	s_barrier
	v_mfma_f32_16x16x32_bf16 v[60:63], v[128:131], v[160:163], v[60:63]
	v_mfma_f32_16x16x32_bf16 v[56:59], v[136:139], v[160:163], v[56:59]
	v_mfma_f32_16x16x32_bf16 v[44:47], v[128:131], v[168:171], v[44:47]
	v_mfma_f32_16x16x32_bf16 v[40:43], v[136:139], v[168:171], v[40:43]
	v_mfma_f32_16x16x32_bf16 v[28:31], v[128:131], v[192:195], v[28:31]
	v_mfma_f32_16x16x32_bf16 v[24:27], v[136:139], v[192:195], v[24:27]
	v_mfma_f32_16x16x32_bf16 v[12:15], v[128:131], v[200:203], v[12:15]
	v_mfma_f32_16x16x32_bf16 v[8:11], v[136:139], v[200:203], v[8:11]
	v_mfma_f32_16x16x32_bf16 v[60:63], v[132:135], v[164:167], v[60:63]
	v_mfma_f32_16x16x32_bf16 v[56:59], v[140:143], v[164:167], v[56:59]
	v_mfma_f32_16x16x32_bf16 v[44:47], v[132:135], v[172:175], v[44:47]
	v_mfma_f32_16x16x32_bf16 v[40:43], v[140:143], v[172:175], v[40:43]
	v_mfma_f32_16x16x32_bf16 v[28:31], v[132:135], v[196:199], v[28:31]
	v_mfma_f32_16x16x32_bf16 v[24:27], v[140:143], v[196:199], v[24:27]
	v_mfma_f32_16x16x32_bf16 v[12:15], v[132:135], v[204:207], v[12:15]
	v_mfma_f32_16x16x32_bf16 v[8:11], v[140:143], v[204:207], v[8:11]
	v_mfma_f32_16x16x32_bf16 v[52:55], v[144:147], v[160:163], v[52:55]
	v_mfma_f32_16x16x32_bf16 v[48:51], v[152:155], v[160:163], v[48:51]
	v_mfma_f32_16x16x32_bf16 v[36:39], v[144:147], v[168:171], v[36:39]
	v_mfma_f32_16x16x32_bf16 v[32:35], v[152:155], v[168:171], v[32:35]
	v_mfma_f32_16x16x32_bf16 v[20:23], v[144:147], v[192:195], v[20:23]
	v_mfma_f32_16x16x32_bf16 v[16:19], v[152:155], v[192:195], v[16:19]
	v_mfma_f32_16x16x32_bf16 v[4:7], v[144:147], v[200:203], v[4:7]
	v_mfma_f32_16x16x32_bf16 v[0:3], v[152:155], v[200:203], v[0:3]
	v_mfma_f32_16x16x32_bf16 v[52:55], v[148:151], v[164:167], v[52:55]
	v_mfma_f32_16x16x32_bf16 v[48:51], v[156:159], v[164:167], v[48:51]
	v_mfma_f32_16x16x32_bf16 v[36:39], v[148:151], v[172:175], v[36:39]
	v_mfma_f32_16x16x32_bf16 v[32:35], v[156:159], v[172:175], v[32:35]
	v_mfma_f32_16x16x32_bf16 v[20:23], v[148:151], v[196:199], v[20:23]
	v_mfma_f32_16x16x32_bf16 v[16:19], v[156:159], v[196:199], v[16:19]
	v_mfma_f32_16x16x32_bf16 v[4:7], v[148:151], v[204:207], v[4:7]
	v_mfma_f32_16x16x32_bf16 v[0:3], v[156:159], v[204:207], v[0:3]
	s_barrier
	s_add_i32 s58, s58, 2
	s_add_u32 s42, s42, 0x100
	s_addc_u32 s43, s43, 0
	s_add_u32 s25, s25, 0x100
	s_addc_u32 s35, s35, 0
	s_cmp_gt_u32 s58, 29
.LBB0_543:
	ds_read_b128 v[128:131], v216
	ds_read_b128 v[132:135], v216 offset:1024
	ds_read_b128 v[136:139], v216 offset:2048
	ds_read_b128 v[140:143], v216 offset:3072
	ds_read_b128 v[144:147], v217
	ds_read_b128 v[148:151], v217 offset:1024
	ds_read_b128 v[152:155], v217 offset:2048
	ds_read_b128 v[156:159], v217 offset:3072
	s_add_u32 s44, s42, 0xfff80080
	s_addc_u32 s45, s43, -1
	s_cmp_eq_u32 s58, 28
	s_cselect_b32 s47, s0, s45
	s_cselect_b32 s46, s1, s44
	s_cselect_b32 s45, s3, s35
	s_cselect_b32 s44, s9, s25
	s_add_i32 m0, s41, 0xc000
	ds_read_b128 v[160:163], v218
	ds_read_b128 v[164:167], v218 offset:1024
	ds_read_b128 v[168:171], v218 offset:2048
	ds_read_b128 v[172:175], v218 offset:3072
	ds_read_b128 v[192:195], v218 offset:4096
	ds_read_b128 v[196:199], v218 offset:5120
	ds_read_b128 v[200:203], v218 offset:6144
	ds_read_b128 v[204:207], v218 offset:7168
	global_load_lds_dwordx4 v184, s[42:43]
	s_add_i32 m0, s41, 0xe000
	s_nop 0
	global_load_lds_dwordx4 v186, s[42:43]
	s_waitcnt vmcnt(8)
	s_waitcnt lgkmcnt(0)
	s_barrier
	v_mfma_f32_16x16x32_bf16 v[124:127], v[128:131], v[160:163], v[124:127]
	v_mfma_f32_16x16x32_bf16 v[120:123], v[136:139], v[160:163], v[120:123]
	v_mfma_f32_16x16x32_bf16 v[108:111], v[128:131], v[168:171], v[108:111]
	v_mfma_f32_16x16x32_bf16 v[104:107], v[136:139], v[168:171], v[104:107]
	v_mfma_f32_16x16x32_bf16 v[92:95], v[128:131], v[192:195], v[92:95]
	v_mfma_f32_16x16x32_bf16 v[88:91], v[136:139], v[192:195], v[88:91]
	v_mfma_f32_16x16x32_bf16 v[76:79], v[128:131], v[200:203], v[76:79]
	v_mfma_f32_16x16x32_bf16 v[72:75], v[136:139], v[200:203], v[72:75]
	v_mfma_f32_16x16x32_bf16 v[124:127], v[132:135], v[164:167], v[124:127]
	v_mfma_f32_16x16x32_bf16 v[120:123], v[140:143], v[164:167], v[120:123]
	v_mfma_f32_16x16x32_bf16 v[108:111], v[132:135], v[172:175], v[108:111]
	v_mfma_f32_16x16x32_bf16 v[104:107], v[140:143], v[172:175], v[104:107]
	v_mfma_f32_16x16x32_bf16 v[92:95], v[132:135], v[196:199], v[92:95]
	v_mfma_f32_16x16x32_bf16 v[88:91], v[140:143], v[196:199], v[88:91]
	v_mfma_f32_16x16x32_bf16 v[76:79], v[132:135], v[204:207], v[76:79]
	v_mfma_f32_16x16x32_bf16 v[72:75], v[140:143], v[204:207], v[72:75]
	v_mfma_f32_16x16x32_bf16 v[116:119], v[144:147], v[160:163], v[116:119]
	v_mfma_f32_16x16x32_bf16 v[112:115], v[152:155], v[160:163], v[112:115]
	v_mfma_f32_16x16x32_bf16 v[100:103], v[144:147], v[168:171], v[100:103]
	v_mfma_f32_16x16x32_bf16 v[96:99], v[152:155], v[168:171], v[96:99]
	v_mfma_f32_16x16x32_bf16 v[84:87], v[144:147], v[192:195], v[84:87]
	v_mfma_f32_16x16x32_bf16 v[80:83], v[152:155], v[192:195], v[80:83]
	v_mfma_f32_16x16x32_bf16 v[68:71], v[144:147], v[200:203], v[68:71]
	v_mfma_f32_16x16x32_bf16 v[64:67], v[152:155], v[200:203], v[64:67]
	v_mfma_f32_16x16x32_bf16 v[116:119], v[148:151], v[164:167], v[116:119]
	v_mfma_f32_16x16x32_bf16 v[112:115], v[156:159], v[164:167], v[112:115]
	v_mfma_f32_16x16x32_bf16 v[100:103], v[148:151], v[172:175], v[100:103]
	v_mfma_f32_16x16x32_bf16 v[96:99], v[156:159], v[172:175], v[96:99]
	v_mfma_f32_16x16x32_bf16 v[84:87], v[148:151], v[196:199], v[84:87]
	v_mfma_f32_16x16x32_bf16 v[80:83], v[156:159], v[196:199], v[80:83]
	v_mfma_f32_16x16x32_bf16 v[68:71], v[148:151], v[204:207], v[68:71]
	v_mfma_f32_16x16x32_bf16 v[64:67], v[156:159], v[204:207], v[64:67]
	s_barrier
	s_add_i32 s59, s55, s31
	s_add_u32 s98, s44, s20
	s_addc_u32 s99, s45, s21
	s_mov_b32 m0, s59
	ds_read_b128 v[160:163], v218 offset:16384
	ds_read_b128 v[164:167], v218 offset:17408
	ds_read_b128 v[168:171], v218 offset:18432
	ds_read_b128 v[172:175], v218 offset:19456
	ds_read_b128 v[192:195], v218 offset:20480
	ds_read_b128 v[196:199], v218 offset:21504
	ds_read_b128 v[200:203], v218 offset:22528
	ds_read_b128 v[204:207], v218 offset:23552
	global_load_lds_dwordx4 v178, s[44:45]
	s_add_i32 m0, s59, 0x2000
	s_add_u32 s60, s44, 0x80000
	s_addc_u32 s61, s45, 0
	s_add_i32 s59, s56, s31
	global_load_lds_dwordx4 v182, s[44:45]
	s_mov_b32 m0, s59
	s_add_u32 s100, s46, s20
	s_addc_u32 s101, s47, s21
	global_load_lds_dwordx4 v178, s[60:61]
	s_add_i32 m0, s59, 0x2000
	s_nop 0
	global_load_lds_dwordx4 v182, s[60:61]
	s_mov_b32 m0, s41
	s_nop 0
	global_load_lds_dwordx4 v176, s[46:47]
	s_mov_b32 m0, s48
	s_nop 0
	global_load_lds_dwordx4 v180, s[46:47]
	s_waitcnt vmcnt(8)
	s_waitcnt lgkmcnt(0)
	s_barrier
	v_mfma_f32_16x16x32_bf16 v[60:63], v[128:131], v[160:163], v[60:63]
	v_mfma_f32_16x16x32_bf16 v[56:59], v[136:139], v[160:163], v[56:59]
	v_mfma_f32_16x16x32_bf16 v[44:47], v[128:131], v[168:171], v[44:47]
	v_mfma_f32_16x16x32_bf16 v[40:43], v[136:139], v[168:171], v[40:43]
	v_mfma_f32_16x16x32_bf16 v[28:31], v[128:131], v[192:195], v[28:31]
	v_mfma_f32_16x16x32_bf16 v[24:27], v[136:139], v[192:195], v[24:27]
	v_mfma_f32_16x16x32_bf16 v[12:15], v[128:131], v[200:203], v[12:15]
	v_mfma_f32_16x16x32_bf16 v[8:11], v[136:139], v[200:203], v[8:11]
	v_mfma_f32_16x16x32_bf16 v[60:63], v[132:135], v[164:167], v[60:63]
	v_mfma_f32_16x16x32_bf16 v[56:59], v[140:143], v[164:167], v[56:59]
	v_mfma_f32_16x16x32_bf16 v[44:47], v[132:135], v[172:175], v[44:47]
	v_mfma_f32_16x16x32_bf16 v[40:43], v[140:143], v[172:175], v[40:43]
	v_mfma_f32_16x16x32_bf16 v[28:31], v[132:135], v[196:199], v[28:31]
	v_mfma_f32_16x16x32_bf16 v[24:27], v[140:143], v[196:199], v[24:27]
	v_mfma_f32_16x16x32_bf16 v[12:15], v[132:135], v[204:207], v[12:15]
	v_mfma_f32_16x16x32_bf16 v[8:11], v[140:143], v[204:207], v[8:11]
	v_mfma_f32_16x16x32_bf16 v[52:55], v[144:147], v[160:163], v[52:55]
	v_mfma_f32_16x16x32_bf16 v[48:51], v[152:155], v[160:163], v[48:51]
	v_mfma_f32_16x16x32_bf16 v[36:39], v[144:147], v[168:171], v[36:39]
	v_mfma_f32_16x16x32_bf16 v[32:35], v[152:155], v[168:171], v[32:35]
	v_mfma_f32_16x16x32_bf16 v[20:23], v[144:147], v[192:195], v[20:23]
	v_mfma_f32_16x16x32_bf16 v[16:19], v[152:155], v[192:195], v[16:19]
	v_mfma_f32_16x16x32_bf16 v[4:7], v[144:147], v[200:203], v[4:7]
	v_mfma_f32_16x16x32_bf16 v[0:3], v[152:155], v[200:203], v[0:3]
	v_mfma_f32_16x16x32_bf16 v[52:55], v[148:151], v[164:167], v[52:55]
	v_mfma_f32_16x16x32_bf16 v[48:51], v[156:159], v[164:167], v[48:51]
	v_mfma_f32_16x16x32_bf16 v[36:39], v[148:151], v[172:175], v[36:39]
	v_mfma_f32_16x16x32_bf16 v[32:35], v[156:159], v[172:175], v[32:35]
	v_mfma_f32_16x16x32_bf16 v[20:23], v[148:151], v[196:199], v[20:23]
	v_mfma_f32_16x16x32_bf16 v[16:19], v[156:159], v[196:199], v[16:19]
	v_mfma_f32_16x16x32_bf16 v[4:7], v[148:151], v[204:207], v[4:7]
	v_mfma_f32_16x16x32_bf16 v[0:3], v[156:159], v[204:207], v[0:3]
	s_barrier
	s_add_i32 s59, 0, 0x18000
	s_add_i32 s60, 0, 0x1c000
	ds_read_b128 v[128:131], v253
	ds_read_b128 v[132:135], v253 offset:1024
	ds_read_b128 v[136:139], v253 offset:2048
	ds_read_b128 v[140:143], v253 offset:3072
	ds_read_b128 v[144:147], v254
	ds_read_b128 v[148:151], v254 offset:1024
	ds_read_b128 v[152:155], v254 offset:2048
	ds_read_b128 v[156:159], v254 offset:3072
	s_add_u32 s46, s46, 0x80000
	s_addc_u32 s47, s47, 0
	s_mov_b32 m0, s49
	ds_read_b128 v[160:163], v218 offset:32768
	ds_read_b128 v[164:167], v218 offset:33792
	ds_read_b128 v[168:171], v218 offset:34816
	ds_read_b128 v[172:175], v218 offset:35840
	ds_read_b128 v[192:195], v218 offset:36864
	ds_read_b128 v[196:199], v218 offset:37888
	ds_read_b128 v[200:203], v218 offset:38912
	ds_read_b128 v[204:207], v218 offset:39936
	global_load_lds_dwordx4 v176, s[46:47]
	s_mov_b32 m0, s50
	s_nop 0
	global_load_lds_dwordx4 v180, s[46:47]
	s_waitcnt vmcnt(8)
	s_waitcnt lgkmcnt(0)
	s_barrier
	v_mfma_f32_16x16x32_bf16 v[124:127], v[128:131], v[160:163], v[124:127]
	v_mfma_f32_16x16x32_bf16 v[120:123], v[136:139], v[160:163], v[120:123]
	v_mfma_f32_16x16x32_bf16 v[108:111], v[128:131], v[168:171], v[108:111]
	v_mfma_f32_16x16x32_bf16 v[104:107], v[136:139], v[168:171], v[104:107]
	v_mfma_f32_16x16x32_bf16 v[92:95], v[128:131], v[192:195], v[92:95]
	v_mfma_f32_16x16x32_bf16 v[88:91], v[136:139], v[192:195], v[88:91]
	v_mfma_f32_16x16x32_bf16 v[76:79], v[128:131], v[200:203], v[76:79]
	v_mfma_f32_16x16x32_bf16 v[72:75], v[136:139], v[200:203], v[72:75]
	v_mfma_f32_16x16x32_bf16 v[124:127], v[132:135], v[164:167], v[124:127]
	v_mfma_f32_16x16x32_bf16 v[120:123], v[140:143], v[164:167], v[120:123]
	v_mfma_f32_16x16x32_bf16 v[108:111], v[132:135], v[172:175], v[108:111]
	v_mfma_f32_16x16x32_bf16 v[104:107], v[140:143], v[172:175], v[104:107]
	v_mfma_f32_16x16x32_bf16 v[92:95], v[132:135], v[196:199], v[92:95]
	v_mfma_f32_16x16x32_bf16 v[88:91], v[140:143], v[196:199], v[88:91]
	v_mfma_f32_16x16x32_bf16 v[76:79], v[132:135], v[204:207], v[76:79]
	v_mfma_f32_16x16x32_bf16 v[72:75], v[140:143], v[204:207], v[72:75]
	v_mfma_f32_16x16x32_bf16 v[116:119], v[144:147], v[160:163], v[116:119]
	v_mfma_f32_16x16x32_bf16 v[112:115], v[152:155], v[160:163], v[112:115]
	v_mfma_f32_16x16x32_bf16 v[100:103], v[144:147], v[168:171], v[100:103]
	v_mfma_f32_16x16x32_bf16 v[96:99], v[152:155], v[168:171], v[96:99]
	v_mfma_f32_16x16x32_bf16 v[84:87], v[144:147], v[192:195], v[84:87]
	v_mfma_f32_16x16x32_bf16 v[80:83], v[152:155], v[192:195], v[80:83]
	v_mfma_f32_16x16x32_bf16 v[68:71], v[144:147], v[200:203], v[68:71]
	v_mfma_f32_16x16x32_bf16 v[64:67], v[152:155], v[200:203], v[64:67]
	v_mfma_f32_16x16x32_bf16 v[116:119], v[148:151], v[164:167], v[116:119]
	v_mfma_f32_16x16x32_bf16 v[112:115], v[156:159], v[164:167], v[112:115]
	v_mfma_f32_16x16x32_bf16 v[100:103], v[148:151], v[172:175], v[100:103]
	v_mfma_f32_16x16x32_bf16 v[96:99], v[156:159], v[172:175], v[96:99]
	v_mfma_f32_16x16x32_bf16 v[84:87], v[148:151], v[196:199], v[84:87]
	v_mfma_f32_16x16x32_bf16 v[80:83], v[156:159], v[196:199], v[80:83]
	v_mfma_f32_16x16x32_bf16 v[68:71], v[148:151], v[204:207], v[68:71]
	v_mfma_f32_16x16x32_bf16 v[64:67], v[156:159], v[204:207], v[64:67]
	s_barrier
	s_add_i32 s46, s59, s31
	s_mov_b32 m0, s46
	ds_read_b128 v[160:163], v218 offset:49152
	ds_read_b128 v[164:167], v218 offset:50176
	ds_read_b128 v[168:171], v218 offset:51200
	ds_read_b128 v[172:175], v218 offset:52224
	ds_read_b128 v[192:195], v218 offset:53248
	ds_read_b128 v[196:199], v218 offset:54272
	ds_read_b128 v[200:203], v218 offset:55296
	ds_read_b128 v[204:207], v218 offset:56320
	global_load_lds_dwordx4 v178, s[98:99]
	s_add_i32 m0, s46, 0x2000
	s_add_u32 s44, s44, 0x80080
	s_addc_u32 s45, s45, 0
	s_add_i32 s46, s60, s31
	global_load_lds_dwordx4 v182, s[98:99]
	s_mov_b32 m0, s46
	s_nop 0
	global_load_lds_dwordx4 v178, s[44:45]
	s_add_i32 m0, s46, 0x2000
	s_nop 0
	global_load_lds_dwordx4 v182, s[44:45]
	s_mov_b32 m0, s52
	s_nop 0
	global_load_lds_dwordx4 v176, s[100:101]
	s_mov_b32 m0, s53
	s_nop 0
	global_load_lds_dwordx4 v180, s[100:101]
	s_waitcnt vmcnt(8)
	s_waitcnt lgkmcnt(0)
	s_barrier
	v_mfma_f32_16x16x32_bf16 v[60:63], v[128:131], v[160:163], v[60:63]
	v_mfma_f32_16x16x32_bf16 v[56:59], v[136:139], v[160:163], v[56:59]
	v_mfma_f32_16x16x32_bf16 v[44:47], v[128:131], v[168:171], v[44:47]
	v_mfma_f32_16x16x32_bf16 v[40:43], v[136:139], v[168:171], v[40:43]
	v_mfma_f32_16x16x32_bf16 v[28:31], v[128:131], v[192:195], v[28:31]
	v_mfma_f32_16x16x32_bf16 v[24:27], v[136:139], v[192:195], v[24:27]
	v_mfma_f32_16x16x32_bf16 v[12:15], v[128:131], v[200:203], v[12:15]
	v_mfma_f32_16x16x32_bf16 v[8:11], v[136:139], v[200:203], v[8:11]
	v_mfma_f32_16x16x32_bf16 v[60:63], v[132:135], v[164:167], v[60:63]
	v_mfma_f32_16x16x32_bf16 v[56:59], v[140:143], v[164:167], v[56:59]
	v_mfma_f32_16x16x32_bf16 v[44:47], v[132:135], v[172:175], v[44:47]
	v_mfma_f32_16x16x32_bf16 v[40:43], v[140:143], v[172:175], v[40:43]
	v_mfma_f32_16x16x32_bf16 v[28:31], v[132:135], v[196:199], v[28:31]
	v_mfma_f32_16x16x32_bf16 v[24:27], v[140:143], v[196:199], v[24:27]
	v_mfma_f32_16x16x32_bf16 v[12:15], v[132:135], v[204:207], v[12:15]
	v_mfma_f32_16x16x32_bf16 v[8:11], v[140:143], v[204:207], v[8:11]
	v_mfma_f32_16x16x32_bf16 v[52:55], v[144:147], v[160:163], v[52:55]
	v_mfma_f32_16x16x32_bf16 v[48:51], v[152:155], v[160:163], v[48:51]
	v_mfma_f32_16x16x32_bf16 v[36:39], v[144:147], v[168:171], v[36:39]
	v_mfma_f32_16x16x32_bf16 v[32:35], v[152:155], v[168:171], v[32:35]
	v_mfma_f32_16x16x32_bf16 v[20:23], v[144:147], v[192:195], v[20:23]
	v_mfma_f32_16x16x32_bf16 v[16:19], v[152:155], v[192:195], v[16:19]
	v_mfma_f32_16x16x32_bf16 v[4:7], v[144:147], v[200:203], v[4:7]
	v_mfma_f32_16x16x32_bf16 v[0:3], v[152:155], v[200:203], v[0:3]
	v_mfma_f32_16x16x32_bf16 v[52:55], v[148:151], v[164:167], v[52:55]
	v_mfma_f32_16x16x32_bf16 v[48:51], v[156:159], v[164:167], v[48:51]
	v_mfma_f32_16x16x32_bf16 v[36:39], v[148:151], v[172:175], v[36:39]
	v_mfma_f32_16x16x32_bf16 v[32:35], v[156:159], v[172:175], v[32:35]
	v_mfma_f32_16x16x32_bf16 v[20:23], v[148:151], v[196:199], v[20:23]
	v_mfma_f32_16x16x32_bf16 v[16:19], v[156:159], v[196:199], v[16:19]
	v_mfma_f32_16x16x32_bf16 v[4:7], v[148:151], v[204:207], v[4:7]
	v_mfma_f32_16x16x32_bf16 v[0:3], v[156:159], v[204:207], v[0:3]
	s_barrier
	s_add_i32 s58, s58, 2
	s_add_u32 s42, s42, 0x100
	s_addc_u32 s43, s43, 0
	s_add_u32 s25, s25, 0x100
	s_addc_u32 s35, s35, 0
	s_cmp_gt_u32 s58, 29
	s_cbranch_scc0 .LBB0_543
	s_setprio 0
	s_and_b64 vcc, exec, s[22:23]
	s_cbranch_vccz .LBB0_546
	s_barrier

.LBB0_624:
	s_add_u32 s38, s12, 0x6000000
	s_mov_b64 s[40:41], 0x80
	s_addc_u32 s39, s13, 0
	s_add_i32 m0, s72, 0x18000
	v_lshl_add_u64 v[8:9], v[8:9], 0, s[40:41]
	s_lshl_b32 s12, s3, 13
	s_lshl_b32 s79, s1, 5
	s_lshl_b32 s13, s1, 12
	s_waitcnt vmcnt(2)
	s_barrier
	global_load_lds_dwordx4 v[8:9], off
	v_lshl_add_u64 v[6:7], v[6:7], 0, s[40:41]
	s_add_i32 m0, s72, 0x1a000
	s_add_i32 s82, s72, 0x8000
	s_add_i32 s83, s72, 0xa000
	global_load_lds_dwordx4 v[6:7], off
	v_lshl_add_u64 v[4:5], v[4:5], 0, s[40:41]
	s_mov_b32 m0, s82
	s_add_u32 s6, s10, 0x80080
	global_load_lds_dwordx4 v[4:5], off
	v_lshl_add_u64 v[2:3], v[2:3], 0, s[40:41]
	s_mov_b32 m0, s83
	s_addc_u32 s7, s11, 0
	global_load_lds_dwordx4 v[2:3], off
	s_add_i32 m0, s72, 0x1c000
	v_lshl_add_u64 v[2:3], s[6:7], 0, v[154:155]
	global_load_lds_dwordx4 v[2:3], off
	v_lshl_add_u64 v[2:3], s[6:7], 0, v[158:159]
	s_add_i32 m0, s72, 0x1e000
	s_movk_i32 s6, 0x3c0
	global_load_lds_dwordx4 v[2:3], off
	v_lshlrev_b32_e32 v2, 4, v193
	v_lshlrev_b32_e32 v3, 6, v1
	v_lshlrev_b32_e32 v1, 2, v1
	v_and_or_b32 v3, v3, s6, v2
	v_and_b32_e32 v1, 32, v1
	v_bitop3_b32 v3, v3, s12, v1 bitop3:0xde
	v_lshl_or_b32 v1, v192, 6, v2
	v_lshlrev_b32_e32 v2, 2, v192
	v_and_b32_e32 v2, 32, v2
	v_bitop3_b32 v196, v1, s13, v2 bitop3:0xde
	v_add_u32_e32 v253, 0x18000, v196
	v_add_u32_e32 v254, 0x1c000, v196
	s_cmpk_lt_u32 s0, 0x100
	v_mov_b32_e32 v1, v155
	s_cselect_b64 s[42:43], -1, 0
	s_and_b32 s0, s0, 0xffffff00
	s_lshl_b32 s1, s1, 6
	s_lshl_b32 s85, s3, 7
	v_lshl_add_u64 v[160:161], s[4:5], 0, v[0:1]
	v_lshlrev_b32_e32 v0, 15, v10
	s_or_b32 s84, s1, s0
	s_add_i32 s0, s85, 0x100
	v_and_b32_e32 v0, 0xffff0000, v0
	s_cmp_gt_i32 s3, 0
	v_lshl_add_u32 v0, v11, 12, v0
	v_and_b32_e32 v1, 1, v10
	s_cselect_b64 s[44:45], -1, 0
	s_cmp_lt_i32 s3, 3
	v_lshl_or_b32 v0, v1, 6, v0
	s_cselect_b64 s[46:47], -1, 0
	s_lshl_b32 s1, s3, 9
	s_add_i32 s86, s65, 0x80
	v_lshl_add_u32 v162, v12, 1, v0
	v_lshlrev_b32_e32 v0, 15, v13
	s_cmp_gt_i32 s3, -2
	v_and_b32_e32 v0, 0xffff0000, v0
	s_waitcnt vmcnt(6)
	s_cselect_b64 s[48:49], -1, 0
	s_cmp_lt_i32 s3, 1
	v_lshl_add_u32 v0, v14, 12, v0
	v_and_b32_e32 v1, 1, v13
	s_cselect_b64 s[50:51], -1, 0
	s_add_i32 s87, s1, 0x400
	s_add_i32 s89, 0, 0x20000
	s_add_i32 s93, 0, 0x20600
	v_lshl_or_b32 v0, v1, 6, v0
	s_add_i32 s94, 0, 0x10000
	s_add_i32 s95, 0, 0x14000
	s_ashr_i32 s88, s53, 31
	s_add_i32 s90, s89, s1
	s_add_i32 s91, s93, s1
	s_add_i32 s92, s89, s87
	s_add_i32 s93, s93, s87
	v_mov_b32_e32 v163, v155
	v_lshl_add_u32 v164, v15, 1, v0
	v_mov_b32_e32 v165, v155
	v_mov_b64_e32 v[166:167], 0xaeb
	v_mov_b64_e32 v[168:169], 0xaea
	v_add_u32_e32 v197, s94, v196
	v_add_u32_e32 v198, s95, v196
	v_add_u32_e32 v199, 0, v3
	s_add_i32 s96, 0, 0x21400
	v_mov_b32_e32 v200, 0x358637bd
	s_add_i32 s97, 0, 0x20800
	s_lshl_b32 s0, s0, 2
	s_mov_b32 s52, 0x3e6d3388
	s_mov_b32 s54, 0x3f07dc22
	s_mov_b32 s56, 0xbf3a00e3
	v_mov_b32_e32 v246, s56
	s_mov_b32 s58, 0x3f35f0e3
	s_mov_b32 s60, 0xbe11a98e
	s_mov_b32 s62, 0x3e027906
	s_mov_b32 s64, 0xbf38aa3b
	s_movk_i32 s31, 0x2b00
	s_movk_i32 s80, 0x1fff
	s_movk_i32 s81, 0x1ff0
	s_movk_i32 s26, 0x1fe0
	s_movk_i32 s27, 0x1fd0
	s_barrier
	s_branch .LBB0_627

.Lkprio_2:
	ds_read_b128 v[148:151], v197
	ds_read_b128 v[170:173], v197 offset:1024
	ds_read_b128 v[174:177], v197 offset:2048
	ds_read_b128 v[178:181], v197 offset:3072
	ds_read_b128 v[182:185], v198
	ds_read_b128 v[186:189], v198 offset:1024
	ds_read_b128 v[202:205], v198 offset:2048
	ds_read_b128 v[206:209], v198 offset:3072
	s_add_u32 s8, s6, 0xfff80080
	s_addc_u32 s9, s7, -1
	s_cmp_eq_u32 s15, 28
	s_cselect_b32 s11, s69, s9
	s_cselect_b32 s10, s68, s8
	s_cselect_b32 s9, s1, s13
	s_cselect_b32 s8, s3, s12
	s_add_i32 m0, s72, 0xc000
	ds_read_b128 v[214:217], v199
	ds_read_b128 v[218:221], v199 offset:1024
	ds_read_b128 v[222:225], v199 offset:2048
	ds_read_b128 v[226:229], v199 offset:3072
	ds_read_b128 v[230:233], v199 offset:4096
	ds_read_b128 v[234:237], v199 offset:5120
	ds_read_b128 v[238:241], v199 offset:6144
	ds_read_b128 v[242:245], v199 offset:7168
	global_load_lds_dwordx4 v162, s[6:7]
	s_add_i32 m0, s72, 0xe000
	s_nop 0
	global_load_lds_dwordx4 v164, s[6:7]
	s_waitcnt vmcnt(8)
	s_waitcnt lgkmcnt(0)
	s_barrier
	v_mfma_f32_16x16x32_bf16 v[112:115], v[148:151], v[214:217], 0
	v_mfma_f32_16x16x32_bf16 v[80:83], v[174:177], v[214:217], 0
	v_mfma_f32_16x16x32_bf16 v[116:119], v[148:151], v[222:225], 0
	v_mfma_f32_16x16x32_bf16 v[88:91], v[174:177], v[222:225], 0
	v_mfma_f32_16x16x32_bf16 v[124:127], v[148:151], v[230:233], 0
	v_mfma_f32_16x16x32_bf16 v[92:95], v[174:177], v[230:233], 0
	v_mfma_f32_16x16x32_bf16 v[120:123], v[148:151], v[238:241], 0
	v_mfma_f32_16x16x32_bf16 v[84:87], v[174:177], v[238:241], 0
	v_mfma_f32_16x16x32_bf16 v[112:115], v[170:173], v[218:221], v[112:115]
	v_mfma_f32_16x16x32_bf16 v[80:83], v[178:181], v[218:221], v[80:83]
	v_mfma_f32_16x16x32_bf16 v[116:119], v[170:173], v[226:229], v[116:119]
	v_mfma_f32_16x16x32_bf16 v[88:91], v[178:181], v[226:229], v[88:91]
	v_mfma_f32_16x16x32_bf16 v[124:127], v[170:173], v[234:237], v[124:127]
	v_mfma_f32_16x16x32_bf16 v[92:95], v[178:181], v[234:237], v[92:95]
	v_mfma_f32_16x16x32_bf16 v[120:123], v[170:173], v[242:245], v[120:123]
	v_mfma_f32_16x16x32_bf16 v[84:87], v[178:181], v[242:245], v[84:87]
	v_mfma_f32_16x16x32_bf16 v[108:111], v[182:185], v[214:217], 0
	v_mfma_f32_16x16x32_bf16 v[76:79], v[202:205], v[214:217], 0
	v_mfma_f32_16x16x32_bf16 v[104:107], v[182:185], v[222:225], 0
	v_mfma_f32_16x16x32_bf16 v[72:75], v[202:205], v[222:225], 0
	v_mfma_f32_16x16x32_bf16 v[100:103], v[182:185], v[230:233], 0
	v_mfma_f32_16x16x32_bf16 v[68:71], v[202:205], v[230:233], 0
	v_mfma_f32_16x16x32_bf16 v[96:99], v[182:185], v[238:241], 0
	v_mfma_f32_16x16x32_bf16 v[64:67], v[202:205], v[238:241], 0
	v_mfma_f32_16x16x32_bf16 v[108:111], v[186:189], v[218:221], v[108:111]
	v_mfma_f32_16x16x32_bf16 v[76:79], v[206:209], v[218:221], v[76:79]
	v_mfma_f32_16x16x32_bf16 v[104:107], v[186:189], v[226:229], v[104:107]
	v_mfma_f32_16x16x32_bf16 v[72:75], v[206:209], v[226:229], v[72:75]
	v_mfma_f32_16x16x32_bf16 v[100:103], v[186:189], v[234:237], v[100:103]
	v_mfma_f32_16x16x32_bf16 v[68:71], v[206:209], v[234:237], v[68:71]
	v_mfma_f32_16x16x32_bf16 v[96:99], v[186:189], v[242:245], v[96:99]
	v_mfma_f32_16x16x32_bf16 v[64:67], v[206:209], v[242:245], v[64:67]
	s_barrier
	s_add_i32 s16, s94, s63
	s_add_u32 s98, s8, s40
	s_addc_u32 s99, s9, s41
	s_mov_b32 m0, s16
	ds_read_b128 v[214:217], v199 offset:16384
	ds_read_b128 v[218:221], v199 offset:17408
	ds_read_b128 v[222:225], v199 offset:18432
	ds_read_b128 v[226:229], v199 offset:19456
	ds_read_b128 v[230:233], v199 offset:20480
	ds_read_b128 v[234:237], v199 offset:21504
	ds_read_b128 v[238:241], v199 offset:22528
	ds_read_b128 v[242:245], v199 offset:23552
	global_load_lds_dwordx4 v154, s[8:9]
	s_add_i32 m0, s16, 0x2000
	s_add_u32 s16, s8, 0x80000
	s_addc_u32 s17, s9, 0
	s_add_i32 s18, s95, s63
	global_load_lds_dwordx4 v158, s[8:9]
	s_mov_b32 m0, s18
	s_add_u32 s100, s10, s40
	s_addc_u32 s101, s11, s41
	global_load_lds_dwordx4 v154, s[16:17]
	s_add_i32 m0, s18, 0x2000
	s_nop 0
	global_load_lds_dwordx4 v158, s[16:17]
	s_mov_b32 m0, s72
	s_nop 0
	global_load_lds_dwordx4 v152, s[10:11]
	s_mov_b32 m0, s73
	s_nop 0
	global_load_lds_dwordx4 v156, s[10:11]
	s_waitcnt vmcnt(8)
	s_waitcnt lgkmcnt(0)
	s_barrier
	v_mfma_f32_16x16x32_bf16 v[48:51], v[148:151], v[214:217], 0
	v_mfma_f32_16x16x32_bf16 v[16:19], v[174:177], v[214:217], 0
	v_mfma_f32_16x16x32_bf16 v[52:55], v[148:151], v[222:225], 0
	v_mfma_f32_16x16x32_bf16 v[24:27], v[174:177], v[222:225], 0
	v_mfma_f32_16x16x32_bf16 v[60:63], v[148:151], v[230:233], 0
	v_mfma_f32_16x16x32_bf16 v[28:31], v[174:177], v[230:233], 0
	v_mfma_f32_16x16x32_bf16 v[56:59], v[148:151], v[238:241], 0
	v_mfma_f32_16x16x32_bf16 v[20:23], v[174:177], v[238:241], 0
	v_mfma_f32_16x16x32_bf16 v[48:51], v[170:173], v[218:221], v[48:51]
	v_mfma_f32_16x16x32_bf16 v[16:19], v[178:181], v[218:221], v[16:19]
	v_mfma_f32_16x16x32_bf16 v[52:55], v[170:173], v[226:229], v[52:55]
	v_mfma_f32_16x16x32_bf16 v[24:27], v[178:181], v[226:229], v[24:27]
	v_mfma_f32_16x16x32_bf16 v[60:63], v[170:173], v[234:237], v[60:63]
	v_mfma_f32_16x16x32_bf16 v[28:31], v[178:181], v[234:237], v[28:31]
	v_mfma_f32_16x16x32_bf16 v[56:59], v[170:173], v[242:245], v[56:59]
	v_mfma_f32_16x16x32_bf16 v[20:23], v[178:181], v[242:245], v[20:23]
	v_mfma_f32_16x16x32_bf16 v[44:47], v[182:185], v[214:217], 0
	v_mfma_f32_16x16x32_bf16 v[12:15], v[202:205], v[214:217], 0
	v_mfma_f32_16x16x32_bf16 v[40:43], v[182:185], v[222:225], 0
	v_mfma_f32_16x16x32_bf16 v[8:11], v[202:205], v[222:225], 0
	v_mfma_f32_16x16x32_bf16 v[36:39], v[182:185], v[230:233], 0
	v_mfma_f32_16x16x32_bf16 v[4:7], v[202:205], v[230:233], 0
	v_mfma_f32_16x16x32_bf16 v[32:35], v[182:185], v[238:241], 0
	v_mfma_f32_16x16x32_bf16 v[0:3], v[202:205], v[238:241], 0
	v_mfma_f32_16x16x32_bf16 v[44:47], v[186:189], v[218:221], v[44:47]
	v_mfma_f32_16x16x32_bf16 v[12:15], v[206:209], v[218:221], v[12:15]
	v_mfma_f32_16x16x32_bf16 v[40:43], v[186:189], v[226:229], v[40:43]
	v_mfma_f32_16x16x32_bf16 v[8:11], v[206:209], v[226:229], v[8:11]
	v_mfma_f32_16x16x32_bf16 v[36:39], v[186:189], v[234:237], v[36:39]
	v_mfma_f32_16x16x32_bf16 v[4:7], v[206:209], v[234:237], v[4:7]
	v_mfma_f32_16x16x32_bf16 v[32:35], v[186:189], v[242:245], v[32:35]
	v_mfma_f32_16x16x32_bf16 v[0:3], v[206:209], v[242:245], v[0:3]
	s_barrier
	s_add_i32 s16, 0, 0x18000
	s_add_i32 s17, 0, 0x1c000
	ds_read_b128 v[148:151], v253
	ds_read_b128 v[170:173], v253 offset:1024
	ds_read_b128 v[174:177], v253 offset:2048
	ds_read_b128 v[178:181], v253 offset:3072
	ds_read_b128 v[182:185], v254
	ds_read_b128 v[186:189], v254 offset:1024
	ds_read_b128 v[202:205], v254 offset:2048
	ds_read_b128 v[206:209], v254 offset:3072
	s_add_u32 s10, s10, 0x80000
	s_addc_u32 s11, s11, 0
	s_mov_b32 m0, s74
	ds_read_b128 v[214:217], v199 offset:32768
	ds_read_b128 v[218:221], v199 offset:33792
	ds_read_b128 v[222:225], v199 offset:34816
	ds_read_b128 v[226:229], v199 offset:35840
	ds_read_b128 v[230:233], v199 offset:36864
	ds_read_b128 v[234:237], v199 offset:37888
	ds_read_b128 v[238:241], v199 offset:38912
	ds_read_b128 v[242:245], v199 offset:39936
	global_load_lds_dwordx4 v152, s[10:11]
	s_mov_b32 m0, s75
	s_nop 0
	global_load_lds_dwordx4 v156, s[10:11]
	s_waitcnt vmcnt(8)
	s_waitcnt lgkmcnt(0)
	s_barrier
	v_mfma_f32_16x16x32_bf16 v[112:115], v[148:151], v[214:217], v[112:115]
	v_mfma_f32_16x16x32_bf16 v[80:83], v[174:177], v[214:217], v[80:83]
	v_mfma_f32_16x16x32_bf16 v[116:119], v[148:151], v[222:225], v[116:119]
	v_mfma_f32_16x16x32_bf16 v[88:91], v[174:177], v[222:225], v[88:91]
	v_mfma_f32_16x16x32_bf16 v[124:127], v[148:151], v[230:233], v[124:127]
	v_mfma_f32_16x16x32_bf16 v[92:95], v[174:177], v[230:233], v[92:95]
	v_mfma_f32_16x16x32_bf16 v[120:123], v[148:151], v[238:241], v[120:123]
	v_mfma_f32_16x16x32_bf16 v[84:87], v[174:177], v[238:241], v[84:87]
	v_mfma_f32_16x16x32_bf16 v[112:115], v[170:173], v[218:221], v[112:115]
	v_mfma_f32_16x16x32_bf16 v[80:83], v[178:181], v[218:221], v[80:83]
	v_mfma_f32_16x16x32_bf16 v[116:119], v[170:173], v[226:229], v[116:119]
	v_mfma_f32_16x16x32_bf16 v[88:91], v[178:181], v[226:229], v[88:91]
	v_mfma_f32_16x16x32_bf16 v[124:127], v[170:173], v[234:237], v[124:127]
	v_mfma_f32_16x16x32_bf16 v[92:95], v[178:181], v[234:237], v[92:95]
	v_mfma_f32_16x16x32_bf16 v[120:123], v[170:173], v[242:245], v[120:123]
	v_mfma_f32_16x16x32_bf16 v[84:87], v[178:181], v[242:245], v[84:87]
	v_mfma_f32_16x16x32_bf16 v[108:111], v[182:185], v[214:217], v[108:111]
	v_mfma_f32_16x16x32_bf16 v[76:79], v[202:205], v[214:217], v[76:79]
	v_mfma_f32_16x16x32_bf16 v[104:107], v[182:185], v[222:225], v[104:107]
	v_mfma_f32_16x16x32_bf16 v[72:75], v[202:205], v[222:225], v[72:75]
	v_mfma_f32_16x16x32_bf16 v[100:103], v[182:185], v[230:233], v[100:103]
	v_mfma_f32_16x16x32_bf16 v[68:71], v[202:205], v[230:233], v[68:71]
	v_mfma_f32_16x16x32_bf16 v[96:99], v[182:185], v[238:241], v[96:99]
	v_mfma_f32_16x16x32_bf16 v[64:67], v[202:205], v[238:241], v[64:67]
	v_mfma_f32_16x16x32_bf16 v[108:111], v[186:189], v[218:221], v[108:111]
	v_mfma_f32_16x16x32_bf16 v[76:79], v[206:209], v[218:221], v[76:79]
	v_mfma_f32_16x16x32_bf16 v[104:107], v[186:189], v[226:229], v[104:107]
	v_mfma_f32_16x16x32_bf16 v[72:75], v[206:209], v[226:229], v[72:75]
	v_mfma_f32_16x16x32_bf16 v[100:103], v[186:189], v[234:237], v[100:103]
	v_mfma_f32_16x16x32_bf16 v[68:71], v[206:209], v[234:237], v[68:71]
	v_mfma_f32_16x16x32_bf16 v[96:99], v[186:189], v[242:245], v[96:99]
	v_mfma_f32_16x16x32_bf16 v[64:67], v[206:209], v[242:245], v[64:67]
	s_barrier
	s_add_i32 s10, s16, s63
	s_mov_b32 m0, s10
	ds_read_b128 v[214:217], v199 offset:49152
	ds_read_b128 v[218:221], v199 offset:50176
	ds_read_b128 v[222:225], v199 offset:51200
	ds_read_b128 v[226:229], v199 offset:52224
	ds_read_b128 v[230:233], v199 offset:53248
	ds_read_b128 v[234:237], v199 offset:54272
	ds_read_b128 v[238:241], v199 offset:55296
	ds_read_b128 v[242:245], v199 offset:56320
	global_load_lds_dwordx4 v154, s[98:99]
	s_add_i32 m0, s10, 0x2000
	s_add_u32 s8, s8, 0x80080
	s_addc_u32 s9, s9, 0
	s_add_i32 s10, s17, s63
	global_load_lds_dwordx4 v158, s[98:99]
	s_mov_b32 m0, s10
	s_nop 0
	global_load_lds_dwordx4 v154, s[8:9]
	s_add_i32 m0, s10, 0x2000
	s_nop 0
	global_load_lds_dwordx4 v158, s[8:9]
	s_mov_b32 m0, s82
	s_nop 0
	global_load_lds_dwordx4 v152, s[100:101]
	s_mov_b32 m0, s83
	s_nop 0
	global_load_lds_dwordx4 v156, s[100:101]
	s_waitcnt vmcnt(8)
	s_waitcnt lgkmcnt(0)
	s_barrier
	v_mfma_f32_16x16x32_bf16 v[48:51], v[148:151], v[214:217], v[48:51]
	v_mfma_f32_16x16x32_bf16 v[16:19], v[174:177], v[214:217], v[16:19]
	v_mfma_f32_16x16x32_bf16 v[52:55], v[148:151], v[222:225], v[52:55]
	v_mfma_f32_16x16x32_bf16 v[24:27], v[174:177], v[222:225], v[24:27]
	v_mfma_f32_16x16x32_bf16 v[60:63], v[148:151], v[230:233], v[60:63]
	v_mfma_f32_16x16x32_bf16 v[28:31], v[174:177], v[230:233], v[28:31]
	v_mfma_f32_16x16x32_bf16 v[56:59], v[148:151], v[238:241], v[56:59]
	v_mfma_f32_16x16x32_bf16 v[20:23], v[174:177], v[238:241], v[20:23]
	v_mfma_f32_16x16x32_bf16 v[48:51], v[170:173], v[218:221], v[48:51]
	v_mfma_f32_16x16x32_bf16 v[16:19], v[178:181], v[218:221], v[16:19]
	v_mfma_f32_16x16x32_bf16 v[52:55], v[170:173], v[226:229], v[52:55]
	v_mfma_f32_16x16x32_bf16 v[24:27], v[178:181], v[226:229], v[24:27]
	v_mfma_f32_16x16x32_bf16 v[60:63], v[170:173], v[234:237], v[60:63]
	v_mfma_f32_16x16x32_bf16 v[28:31], v[178:181], v[234:237], v[28:31]
	v_mfma_f32_16x16x32_bf16 v[56:59], v[170:173], v[242:245], v[56:59]
	v_mfma_f32_16x16x32_bf16 v[20:23], v[178:181], v[242:245], v[20:23]
	v_mfma_f32_16x16x32_bf16 v[44:47], v[182:185], v[214:217], v[44:47]
	v_mfma_f32_16x16x32_bf16 v[12:15], v[202:205], v[214:217], v[12:15]
	v_mfma_f32_16x16x32_bf16 v[40:43], v[182:185], v[222:225], v[40:43]
	v_mfma_f32_16x16x32_bf16 v[8:11], v[202:205], v[222:225], v[8:11]
	v_mfma_f32_16x16x32_bf16 v[36:39], v[182:185], v[230:233], v[36:39]
	v_mfma_f32_16x16x32_bf16 v[4:7], v[202:205], v[230:233], v[4:7]
	v_mfma_f32_16x16x32_bf16 v[32:35], v[182:185], v[238:241], v[32:35]
	v_mfma_f32_16x16x32_bf16 v[0:3], v[202:205], v[238:241], v[0:3]
	v_mfma_f32_16x16x32_bf16 v[44:47], v[186:189], v[218:221], v[44:47]
	v_mfma_f32_16x16x32_bf16 v[12:15], v[206:209], v[218:221], v[12:15]
	v_mfma_f32_16x16x32_bf16 v[40:43], v[186:189], v[226:229], v[40:43]
	v_mfma_f32_16x16x32_bf16 v[8:11], v[206:209], v[226:229], v[8:11]
	v_mfma_f32_16x16x32_bf16 v[36:39], v[186:189], v[234:237], v[36:39]
	v_mfma_f32_16x16x32_bf16 v[4:7], v[206:209], v[234:237], v[4:7]
	v_mfma_f32_16x16x32_bf16 v[32:35], v[186:189], v[242:245], v[32:35]
	v_mfma_f32_16x16x32_bf16 v[0:3], v[206:209], v[242:245], v[0:3]
	s_barrier
	s_add_i32 s15, s15, 2
	s_add_u32 s6, s6, 0x100
	s_addc_u32 s7, s7, 0
	s_add_u32 s12, s12, 0x100
	s_addc_u32 s13, s13, 0
	s_cmp_gt_u32 s15, 29
.LBB0_636:
	ds_read_b128 v[148:151], v197
	ds_read_b128 v[170:173], v197 offset:1024
	ds_read_b128 v[174:177], v197 offset:2048
	ds_read_b128 v[178:181], v197 offset:3072
	ds_read_b128 v[182:185], v198
	ds_read_b128 v[186:189], v198 offset:1024
	ds_read_b128 v[202:205], v198 offset:2048
	ds_read_b128 v[206:209], v198 offset:3072
	s_add_u32 s8, s6, 0xfff80080
	s_addc_u32 s9, s7, -1
	s_cmp_eq_u32 s15, 28
	s_cselect_b32 s11, s69, s9
	s_cselect_b32 s10, s68, s8
	s_cselect_b32 s9, s1, s13
	s_cselect_b32 s8, s3, s12
	s_add_i32 m0, s72, 0xc000
	ds_read_b128 v[214:217], v199
	ds_read_b128 v[218:221], v199 offset:1024
	ds_read_b128 v[222:225], v199 offset:2048
	ds_read_b128 v[226:229], v199 offset:3072
	ds_read_b128 v[230:233], v199 offset:4096
	ds_read_b128 v[234:237], v199 offset:5120
	ds_read_b128 v[238:241], v199 offset:6144
	ds_read_b128 v[242:245], v199 offset:7168
	global_load_lds_dwordx4 v162, s[6:7]
	s_add_i32 m0, s72, 0xe000
	s_nop 0
	global_load_lds_dwordx4 v164, s[6:7]
	s_waitcnt vmcnt(8)
	s_waitcnt lgkmcnt(0)
	s_barrier
	v_mfma_f32_16x16x32_bf16 v[112:115], v[148:151], v[214:217], v[112:115]
	v_mfma_f32_16x16x32_bf16 v[80:83], v[174:177], v[214:217], v[80:83]
	v_mfma_f32_16x16x32_bf16 v[116:119], v[148:151], v[222:225], v[116:119]
	v_mfma_f32_16x16x32_bf16 v[88:91], v[174:177], v[222:225], v[88:91]
	v_mfma_f32_16x16x32_bf16 v[124:127], v[148:151], v[230:233], v[124:127]
	v_mfma_f32_16x16x32_bf16 v[92:95], v[174:177], v[230:233], v[92:95]
	v_mfma_f32_16x16x32_bf16 v[120:123], v[148:151], v[238:241], v[120:123]
	v_mfma_f32_16x16x32_bf16 v[84:87], v[174:177], v[238:241], v[84:87]
	v_mfma_f32_16x16x32_bf16 v[112:115], v[170:173], v[218:221], v[112:115]
	v_mfma_f32_16x16x32_bf16 v[80:83], v[178:181], v[218:221], v[80:83]
	v_mfma_f32_16x16x32_bf16 v[116:119], v[170:173], v[226:229], v[116:119]
	v_mfma_f32_16x16x32_bf16 v[88:91], v[178:181], v[226:229], v[88:91]
	v_mfma_f32_16x16x32_bf16 v[124:127], v[170:173], v[234:237], v[124:127]
	v_mfma_f32_16x16x32_bf16 v[92:95], v[178:181], v[234:237], v[92:95]
	v_mfma_f32_16x16x32_bf16 v[120:123], v[170:173], v[242:245], v[120:123]
	v_mfma_f32_16x16x32_bf16 v[84:87], v[178:181], v[242:245], v[84:87]
	v_mfma_f32_16x16x32_bf16 v[108:111], v[182:185], v[214:217], v[108:111]
	v_mfma_f32_16x16x32_bf16 v[76:79], v[202:205], v[214:217], v[76:79]
	v_mfma_f32_16x16x32_bf16 v[104:107], v[182:185], v[222:225], v[104:107]
	v_mfma_f32_16x16x32_bf16 v[72:75], v[202:205], v[222:225], v[72:75]
	v_mfma_f32_16x16x32_bf16 v[100:103], v[182:185], v[230:233], v[100:103]
	v_mfma_f32_16x16x32_bf16 v[68:71], v[202:205], v[230:233], v[68:71]
	v_mfma_f32_16x16x32_bf16 v[96:99], v[182:185], v[238:241], v[96:99]
	v_mfma_f32_16x16x32_bf16 v[64:67], v[202:205], v[238:241], v[64:67]
	v_mfma_f32_16x16x32_bf16 v[108:111], v[186:189], v[218:221], v[108:111]
	v_mfma_f32_16x16x32_bf16 v[76:79], v[206:209], v[218:221], v[76:79]
	v_mfma_f32_16x16x32_bf16 v[104:107], v[186:189], v[226:229], v[104:107]
	v_mfma_f32_16x16x32_bf16 v[72:75], v[206:209], v[226:229], v[72:75]
	v_mfma_f32_16x16x32_bf16 v[100:103], v[186:189], v[234:237], v[100:103]
	v_mfma_f32_16x16x32_bf16 v[68:71], v[206:209], v[234:237], v[68:71]
	v_mfma_f32_16x16x32_bf16 v[96:99], v[186:189], v[242:245], v[96:99]
	v_mfma_f32_16x16x32_bf16 v[64:67], v[206:209], v[242:245], v[64:67]
	s_barrier
	s_add_i32 s16, s94, s63
	s_add_u32 s98, s8, s40
	s_addc_u32 s99, s9, s41
	s_mov_b32 m0, s16
	ds_read_b128 v[214:217], v199 offset:16384
	ds_read_b128 v[218:221], v199 offset:17408
	ds_read_b128 v[222:225], v199 offset:18432
	ds_read_b128 v[226:229], v199 offset:19456
	ds_read_b128 v[230:233], v199 offset:20480
	ds_read_b128 v[234:237], v199 offset:21504
	ds_read_b128 v[238:241], v199 offset:22528
	ds_read_b128 v[242:245], v199 offset:23552
	global_load_lds_dwordx4 v154, s[8:9]
	s_add_i32 m0, s16, 0x2000
	s_add_u32 s16, s8, 0x80000
	s_addc_u32 s17, s9, 0
	s_add_i32 s18, s95, s63
	global_load_lds_dwordx4 v158, s[8:9]
	s_mov_b32 m0, s18
	s_add_u32 s100, s10, s40
	s_addc_u32 s101, s11, s41
	global_load_lds_dwordx4 v154, s[16:17]
	s_add_i32 m0, s18, 0x2000
	s_nop 0
	global_load_lds_dwordx4 v158, s[16:17]
	s_mov_b32 m0, s72
	s_nop 0
	global_load_lds_dwordx4 v152, s[10:11]
	s_mov_b32 m0, s73
	s_nop 0
	global_load_lds_dwordx4 v156, s[10:11]
	s_waitcnt vmcnt(8)
	s_waitcnt lgkmcnt(0)
	s_barrier
	v_mfma_f32_16x16x32_bf16 v[48:51], v[148:151], v[214:217], v[48:51]
	v_mfma_f32_16x16x32_bf16 v[16:19], v[174:177], v[214:217], v[16:19]
	v_mfma_f32_16x16x32_bf16 v[52:55], v[148:151], v[222:225], v[52:55]
	v_mfma_f32_16x16x32_bf16 v[24:27], v[174:177], v[222:225], v[24:27]
	v_mfma_f32_16x16x32_bf16 v[60:63], v[148:151], v[230:233], v[60:63]
	v_mfma_f32_16x16x32_bf16 v[28:31], v[174:177], v[230:233], v[28:31]
	v_mfma_f32_16x16x32_bf16 v[56:59], v[148:151], v[238:241], v[56:59]
	v_mfma_f32_16x16x32_bf16 v[20:23], v[174:177], v[238:241], v[20:23]
	v_mfma_f32_16x16x32_bf16 v[48:51], v[170:173], v[218:221], v[48:51]
	v_mfma_f32_16x16x32_bf16 v[16:19], v[178:181], v[218:221], v[16:19]
	v_mfma_f32_16x16x32_bf16 v[52:55], v[170:173], v[226:229], v[52:55]
	v_mfma_f32_16x16x32_bf16 v[24:27], v[178:181], v[226:229], v[24:27]
	v_mfma_f32_16x16x32_bf16 v[60:63], v[170:173], v[234:237], v[60:63]
	v_mfma_f32_16x16x32_bf16 v[28:31], v[178:181], v[234:237], v[28:31]
	v_mfma_f32_16x16x32_bf16 v[56:59], v[170:173], v[242:245], v[56:59]
	v_mfma_f32_16x16x32_bf16 v[20:23], v[178:181], v[242:245], v[20:23]
	v_mfma_f32_16x16x32_bf16 v[44:47], v[182:185], v[214:217], v[44:47]
	v_mfma_f32_16x16x32_bf16 v[12:15], v[202:205], v[214:217], v[12:15]
	v_mfma_f32_16x16x32_bf16 v[40:43], v[182:185], v[222:225], v[40:43]
	v_mfma_f32_16x16x32_bf16 v[8:11], v[202:205], v[222:225], v[8:11]
	v_mfma_f32_16x16x32_bf16 v[36:39], v[182:185], v[230:233], v[36:39]
	v_mfma_f32_16x16x32_bf16 v[4:7], v[202:205], v[230:233], v[4:7]
	v_mfma_f32_16x16x32_bf16 v[32:35], v[182:185], v[238:241], v[32:35]
	v_mfma_f32_16x16x32_bf16 v[0:3], v[202:205], v[238:241], v[0:3]
	v_mfma_f32_16x16x32_bf16 v[44:47], v[186:189], v[218:221], v[44:47]
	v_mfma_f32_16x16x32_bf16 v[12:15], v[206:209], v[218:221], v[12:15]
	v_mfma_f32_16x16x32_bf16 v[40:43], v[186:189], v[226:229], v[40:43]
	v_mfma_f32_16x16x32_bf16 v[8:11], v[206:209], v[226:229], v[8:11]
	v_mfma_f32_16x16x32_bf16 v[36:39], v[186:189], v[234:237], v[36:39]
	v_mfma_f32_16x16x32_bf16 v[4:7], v[206:209], v[234:237], v[4:7]
	v_mfma_f32_16x16x32_bf16 v[32:35], v[186:189], v[242:245], v[32:35]
	v_mfma_f32_16x16x32_bf16 v[0:3], v[206:209], v[242:245], v[0:3]
	s_barrier
	s_add_i32 s16, 0, 0x18000
	s_add_i32 s17, 0, 0x1c000
	ds_read_b128 v[148:151], v253
	ds_read_b128 v[170:173], v253 offset:1024
	ds_read_b128 v[174:177], v253 offset:2048
	ds_read_b128 v[178:181], v253 offset:3072
	ds_read_b128 v[182:185], v254
	ds_read_b128 v[186:189], v254 offset:1024
	ds_read_b128 v[202:205], v254 offset:2048
	ds_read_b128 v[206:209], v254 offset:3072
	s_add_u32 s10, s10, 0x80000
	s_addc_u32 s11, s11, 0
	s_mov_b32 m0, s74
	ds_read_b128 v[214:217], v199 offset:32768
	ds_read_b128 v[218:221], v199 offset:33792
	ds_read_b128 v[222:225], v199 offset:34816
	ds_read_b128 v[226:229], v199 offset:35840
	ds_read_b128 v[230:233], v199 offset:36864
	ds_read_b128 v[234:237], v199 offset:37888
	ds_read_b128 v[238:241], v199 offset:38912
	ds_read_b128 v[242:245], v199 offset:39936
	global_load_lds_dwordx4 v152, s[10:11]
	s_mov_b32 m0, s75
	s_nop 0
	global_load_lds_dwordx4 v156, s[10:11]
	s_waitcnt vmcnt(8)
	s_waitcnt lgkmcnt(0)
	s_barrier
	v_mfma_f32_16x16x32_bf16 v[112:115], v[148:151], v[214:217], v[112:115]
	v_mfma_f32_16x16x32_bf16 v[80:83], v[174:177], v[214:217], v[80:83]
	v_mfma_f32_16x16x32_bf16 v[116:119], v[148:151], v[222:225], v[116:119]
	v_mfma_f32_16x16x32_bf16 v[88:91], v[174:177], v[222:225], v[88:91]
	v_mfma_f32_16x16x32_bf16 v[124:127], v[148:151], v[230:233], v[124:127]
	v_mfma_f32_16x16x32_bf16 v[92:95], v[174:177], v[230:233], v[92:95]
	v_mfma_f32_16x16x32_bf16 v[120:123], v[148:151], v[238:241], v[120:123]
	v_mfma_f32_16x16x32_bf16 v[84:87], v[174:177], v[238:241], v[84:87]
	v_mfma_f32_16x16x32_bf16 v[112:115], v[170:173], v[218:221], v[112:115]
	v_mfma_f32_16x16x32_bf16 v[80:83], v[178:181], v[218:221], v[80:83]
	v_mfma_f32_16x16x32_bf16 v[116:119], v[170:173], v[226:229], v[116:119]
	v_mfma_f32_16x16x32_bf16 v[88:91], v[178:181], v[226:229], v[88:91]
	v_mfma_f32_16x16x32_bf16 v[124:127], v[170:173], v[234:237], v[124:127]
	v_mfma_f32_16x16x32_bf16 v[92:95], v[178:181], v[234:237], v[92:95]
	v_mfma_f32_16x16x32_bf16 v[120:123], v[170:173], v[242:245], v[120:123]
	v_mfma_f32_16x16x32_bf16 v[84:87], v[178:181], v[242:245], v[84:87]
	v_mfma_f32_16x16x32_bf16 v[108:111], v[182:185], v[214:217], v[108:111]
	v_mfma_f32_16x16x32_bf16 v[76:79], v[202:205], v[214:217], v[76:79]
	v_mfma_f32_16x16x32_bf16 v[104:107], v[182:185], v[222:225], v[104:107]
	v_mfma_f32_16x16x32_bf16 v[72:75], v[202:205], v[222:225], v[72:75]
	v_mfma_f32_16x16x32_bf16 v[100:103], v[182:185], v[230:233], v[100:103]
	v_mfma_f32_16x16x32_bf16 v[68:71], v[202:205], v[230:233], v[68:71]
	v_mfma_f32_16x16x32_bf16 v[96:99], v[182:185], v[238:241], v[96:99]
	v_mfma_f32_16x16x32_bf16 v[64:67], v[202:205], v[238:241], v[64:67]
	v_mfma_f32_16x16x32_bf16 v[108:111], v[186:189], v[218:221], v[108:111]
	v_mfma_f32_16x16x32_bf16 v[76:79], v[206:209], v[218:221], v[76:79]
	v_mfma_f32_16x16x32_bf16 v[104:107], v[186:189], v[226:229], v[104:107]
	v_mfma_f32_16x16x32_bf16 v[72:75], v[206:209], v[226:229], v[72:75]
	v_mfma_f32_16x16x32_bf16 v[100:103], v[186:189], v[234:237], v[100:103]
	v_mfma_f32_16x16x32_bf16 v[68:71], v[206:209], v[234:237], v[68:71]
	v_mfma_f32_16x16x32_bf16 v[96:99], v[186:189], v[242:245], v[96:99]
	v_mfma_f32_16x16x32_bf16 v[64:67], v[206:209], v[242:245], v[64:67]
	s_barrier
	s_add_i32 s10, s16, s63
	s_mov_b32 m0, s10
	ds_read_b128 v[214:217], v199 offset:49152
	ds_read_b128 v[218:221], v199 offset:50176
	ds_read_b128 v[222:225], v199 offset:51200
	ds_read_b128 v[226:229], v199 offset:52224
	ds_read_b128 v[230:233], v199 offset:53248
	ds_read_b128 v[234:237], v199 offset:54272
	ds_read_b128 v[238:241], v199 offset:55296
	ds_read_b128 v[242:245], v199 offset:56320
	global_load_lds_dwordx4 v154, s[98:99]
	s_add_i32 m0, s10, 0x2000
	s_add_u32 s8, s8, 0x80080
	s_addc_u32 s9, s9, 0
	s_add_i32 s10, s17, s63
	global_load_lds_dwordx4 v158, s[98:99]
	s_mov_b32 m0, s10
	s_nop 0
	global_load_lds_dwordx4 v154, s[8:9]
	s_add_i32 m0, s10, 0x2000
	s_nop 0
	global_load_lds_dwordx4 v158, s[8:9]
	s_mov_b32 m0, s82
	s_nop 0
	global_load_lds_dwordx4 v152, s[100:101]
	s_mov_b32 m0, s83
	s_nop 0
	global_load_lds_dwordx4 v156, s[100:101]
	s_waitcnt vmcnt(8)
	s_waitcnt lgkmcnt(0)
	s_barrier
	v_mfma_f32_16x16x32_bf16 v[48:51], v[148:151], v[214:217], v[48:51]
	v_mfma_f32_16x16x32_bf16 v[16:19], v[174:177], v[214:217], v[16:19]
	v_mfma_f32_16x16x32_bf16 v[52:55], v[148:151], v[222:225], v[52:55]
	v_mfma_f32_16x16x32_bf16 v[24:27], v[174:177], v[222:225], v[24:27]
	v_mfma_f32_16x16x32_bf16 v[60:63], v[148:151], v[230:233], v[60:63]
	v_mfma_f32_16x16x32_bf16 v[28:31], v[174:177], v[230:233], v[28:31]
	v_mfma_f32_16x16x32_bf16 v[56:59], v[148:151], v[238:241], v[56:59]
	v_mfma_f32_16x16x32_bf16 v[20:23], v[174:177], v[238:241], v[20:23]
	v_mfma_f32_16x16x32_bf16 v[48:51], v[170:173], v[218:221], v[48:51]
	v_mfma_f32_16x16x32_bf16 v[16:19], v[178:181], v[218:221], v[16:19]
	v_mfma_f32_16x16x32_bf16 v[52:55], v[170:173], v[226:229], v[52:55]
	v_mfma_f32_16x16x32_bf16 v[24:27], v[178:181], v[226:229], v[24:27]
	v_mfma_f32_16x16x32_bf16 v[60:63], v[170:173], v[234:237], v[60:63]
	v_mfma_f32_16x16x32_bf16 v[28:31], v[178:181], v[234:237], v[28:31]
	v_mfma_f32_16x16x32_bf16 v[56:59], v[170:173], v[242:245], v[56:59]
	v_mfma_f32_16x16x32_bf16 v[20:23], v[178:181], v[242:245], v[20:23]
	v_mfma_f32_16x16x32_bf16 v[44:47], v[182:185], v[214:217], v[44:47]
	v_mfma_f32_16x16x32_bf16 v[12:15], v[202:205], v[214:217], v[12:15]
	v_mfma_f32_16x16x32_bf16 v[40:43], v[182:185], v[222:225], v[40:43]
	v_mfma_f32_16x16x32_bf16 v[8:11], v[202:205], v[222:225], v[8:11]
	v_mfma_f32_16x16x32_bf16 v[36:39], v[182:185], v[230:233], v[36:39]
	v_mfma_f32_16x16x32_bf16 v[4:7], v[202:205], v[230:233], v[4:7]
	v_mfma_f32_16x16x32_bf16 v[32:35], v[182:185], v[238:241], v[32:35]
	v_mfma_f32_16x16x32_bf16 v[0:3], v[202:205], v[238:241], v[0:3]
	v_mfma_f32_16x16x32_bf16 v[44:47], v[186:189], v[218:221], v[44:47]
	v_mfma_f32_16x16x32_bf16 v[12:15], v[206:209], v[218:221], v[12:15]
	v_mfma_f32_16x16x32_bf16 v[40:43], v[186:189], v[226:229], v[40:43]
	v_mfma_f32_16x16x32_bf16 v[8:11], v[206:209], v[226:229], v[8:11]
	v_mfma_f32_16x16x32_bf16 v[36:39], v[186:189], v[234:237], v[36:39]
	v_mfma_f32_16x16x32_bf16 v[4:7], v[206:209], v[234:237], v[4:7]
	v_mfma_f32_16x16x32_bf16 v[32:35], v[186:189], v[242:245], v[32:35]
	v_mfma_f32_16x16x32_bf16 v[0:3], v[206:209], v[242:245], v[0:3]
	s_barrier
	s_add_i32 s15, s15, 2
	s_add_u32 s6, s6, 0x100
	s_addc_u32 s7, s7, 0
	s_add_u32 s12, s12, 0x100
	s_addc_u32 s13, s13, 0
	s_cmp_gt_u32 s15, 29
	s_cbranch_scc0 .LBB0_636
	s_setprio 0
	s_and_b64 vcc, exec, s[42:43]
	s_cbranch_vccz .LBB0_639
	s_barrier
